# sample-FoX: next tile V rows requested at the top of the iteration and K rows two tiles ahead right after the K conversion (whole-iteration load cover); EpiGlu dead DPP old=0 initialisers removed
# speedup vs baseline: 1.0174x; 1.0174x over previous
.LBB0_981:
	s_or_b64 exec, exec, s[40:41]
	s_lshl_b64 s[8:9], s[8:9], 17
	s_add_u32 s40, s4, s8
	s_addc_u32 s41, s5, s9
	s_add_u32 s44, s40, s43
	v_readlane_b32 s60, v245, 0
	s_addc_u32 s45, s41, 0
	s_lshl_b64 s[36:37], s[36:37], 2
	v_readlane_b32 s66, v245, 6
	v_readlane_b32 s67, v245, 7
	s_add_u32 s36, s66, s36
	s_addc_u32 s37, s67, s37
	s_add_u32 s36, s36, s43
	s_addc_u32 s37, s37, 0
	s_add_u32 s8, s14, s8
	s_addc_u32 s9, s15, s9
	v_lshlrev_b64 v[8:9], 9, v[6:7]
	v_lshlrev_b32_e32 v5, 2, v3
	s_add_u32 s48, s8, s43
	s_addc_u32 s49, s9, 0
	s_add_i32 s8, s56, 0x1000
	v_lshl_add_u64 v[8:9], v[8:9], 2, s[36:37]
	v_lshlrev_b32_e32 v198, 2, v5
	v_or_b32_e32 v175, s8, v133
	v_lshl_add_u64 v[8:9], v[8:9], 0, v[198:199]
	s_mov_b32 s8, 0x20000
	v_readlane_b32 s68, v245, 8
	v_add_co_u32_e32 v10, vcc, s8, v8
	s_mov_b32 s68, 0x40000
	s_nop 0
	v_addc_co_u32_e32 v11, vcc, 0, v9, vcc
	global_load_dwordx4 v[106:109], v[8:9], off
	global_load_dwordx4 v[110:113], v[8:9], off offset:128
	global_load_dwordx4 v[98:101], v[10:11], off
	global_load_dwordx4 v[102:105], v[10:11], off offset:128
	v_add_co_u32_e32 v10, vcc, s68, v8
	s_mov_b32 s8, 0x60000
	s_nop 0
	v_addc_co_u32_e32 v11, vcc, 0, v9, vcc
	v_add_co_u32_e32 v8, vcc, s8, v8
	global_load_dwordx4 v[114:117], v[10:11], off
	global_load_dwordx4 v[118:121], v[10:11], off offset:128
	v_addc_co_u32_e32 v9, vcc, 0, v9, vcc
	global_load_dwordx4 v[122:125], v[8:9], off
	global_load_dwordx4 v[126:129], v[8:9], off offset:128
	s_lshl_b32 s43, s39, 6
	v_lshlrev_b32_e32 v49, 2, v1
	v_lshrrev_b32_e32 v12, 2, v4
	v_or_b32_e32 v132, s43, v49
	v_and_or_b32 v1, v12, 3, v132
	v_mul_lo_u32 v1, v1, s82
	v_add_u32_e32 v25, 0, v1
	v_and_b32_e32 v1, 16, v4
	v_lshlrev_b32_e32 v176, 2, v4
	v_or_b32_e32 v5, s43, v133
	v_and_or_b32 v1, v176, 12, v1
	v_mul_lo_u32 v5, v5, s82
	v_lshlrev_b32_e32 v27, 1, v1
	v_mul_lo_u32 v1, v6, s82
	v_add_u32_e32 v23, 0, v5
	v_lshlrev_b32_e32 v28, 2, v132
	v_add_u32_e32 v29, 0, v1
	v_lshlrev_b32_e32 v30, 3, v3
	s_mov_b64 s[8:9], 0x100
	v_mov_b32_e32 v18, v199
	v_mov_b32_e32 v19, v199
	v_add_u32_e32 v138, 0x100, v4
	v_lshl_add_u64 v[142:143], v[6:7], 0, s[8:9]
	v_mov_b32_e32 v4, v199
	v_mov_b32_e32 v5, v199
	v_mov_b32_e32 v6, v199
	v_mov_b32_e32 v7, v199
	v_mov_b32_e32 v8, v199
	v_mov_b32_e32 v9, v199
	v_mov_b32_e32 v10, v199
	v_mov_b32_e32 v11, v199
	v_mov_b32_e32 v12, v199
	v_mov_b32_e32 v13, v199
	v_mov_b32_e32 v14, v199
	v_mov_b32_e32 v15, v199
	v_mov_b32_e32 v16, v199
	v_mov_b32_e32 v17, v199
	v_add_u32_e32 v177, v23, v26
	v_add_u32_e32 v23, 0, v28
	v_add_u32_e32 v179, v25, v27
	v_add_u32_e32 v180, v29, v30
	v_mov_b64_e32 v[40:41], v[18:19]
	s_waitcnt vmcnt(15)
	v_cvt_pk_bf16_f32 v134, v74, v75
	v_cvt_pk_bf16_f32 v135, v76, v77
	s_waitcnt vmcnt(14)
	v_cvt_pk_bf16_f32 v136, v78, v79
	v_cvt_pk_bf16_f32 v137, v80, v81
	s_waitcnt vmcnt(13)
	v_cvt_pk_bf16_f32 v140, v66, v67
	v_cvt_pk_bf16_f32 v141, v68, v69
	s_waitcnt vmcnt(12)
	v_cvt_pk_bf16_f32 v144, v70, v71
	v_cvt_pk_bf16_f32 v145, v72, v73
	s_waitcnt vmcnt(11)
	v_cvt_pk_bf16_f32 v146, v82, v83
	v_cvt_pk_bf16_f32 v147, v84, v85
	s_waitcnt vmcnt(10)
	v_cvt_pk_bf16_f32 v148, v86, v87
	v_cvt_pk_bf16_f32 v149, v88, v89
	s_waitcnt vmcnt(9)
	v_cvt_pk_bf16_f32 v150, v90, v91
	v_cvt_pk_bf16_f32 v151, v92, v93
	s_waitcnt vmcnt(8)
	v_cvt_pk_bf16_f32 v152, v94, v95
	v_cvt_pk_bf16_f32 v153, v96, v97
	v_lshlrev_b64 v[74:75], 11, v[142:143]
	v_lshl_add_u64 v[74:75], s[12:13], 0, v[74:75]
	v_lshl_add_u64 v[154:155], v[74:75], 0, v[198:199]
	global_load_dwordx4 v[74:77], v[154:155], off
	global_load_dwordx4 v[78:81], v[154:155], off offset:128
	v_add_co_u32_e32 v70, vcc, 0x20000, v154
	s_nop 1
	v_addc_co_u32_e32 v71, vcc, 0, v155, vcc
	global_load_dwordx4 v[66:69], v[70:71], off
	s_nop 0
	global_load_dwordx4 v[70:73], v[70:71], off offset:128
	v_add_co_u32_e32 v86, vcc, 0x40000, v154
	s_nop 1
	v_addc_co_u32_e32 v87, vcc, 0, v155, vcc
	global_load_dwordx4 v[82:85], v[86:87], off
	s_nop 0
	global_load_dwordx4 v[86:89], v[86:87], off offset:128
	v_add_co_u32_e32 v94, vcc, 0x60000, v154
	s_nop 1
	v_addc_co_u32_e32 v95, vcc, 0, v155, vcc
	global_load_dwordx4 v[90:93], v[94:95], off
	s_nop 0
	global_load_dwordx4 v[94:97], v[94:95], off offset:128
	s_mov_b32 s50, 0
	s_add_i32 s51, s56, 0x101f
	s_addk_i32 s56, 0xfc1
	v_mov_b32_e32 v1, v2
	v_mov_b32_e32 v20, v2
	v_mov_b32_e32 v3, v2
	v_mov_b32_e32 v22, v2
	v_mov_b32_e32 v21, v2
	v_mov_b32_e32 v24, v2
	v_mov_b32_e32 v181, 0xf149f2ca
	s_mov_b64 s[40:41], 0
	v_add_u32_e32 v178, 0x12000, v23
	v_mov_b32_e32 v50, 0
	v_mov_b32_e32 v51, v173
	v_mov_b32_e32 v52, v173
	v_mov_b32_e32 v53, v173
	v_mov_b32_e32 v58, 0
	v_mov_b32_e32 v59, v173
	v_mov_b32_e32 v60, v173
	v_mov_b32_e32 v61, v173
	v_mov_b32_e32 v54, 0
	v_mov_b32_e32 v55, v173
	v_mov_b32_e32 v56, v173
	v_mov_b32_e32 v57, v173
	v_mov_b32_e32 v62, 0
	v_mov_b32_e32 v63, v173
	v_mov_b32_e32 v64, v173
	v_mov_b32_e32 v65, v173
	v_mov_b32_e32 v23, v2
	v_mov_b32_e32 v42, v2
	v_mov_b32_e32 v25, v2
	v_mov_b32_e32 v44, v2
	v_mov_b32_e32 v43, v2
	v_mov_b32_e32 v46, v2
	v_mov_b32_e32 v45, v2
	v_mov_b32_e32 v48, v2
	v_mov_b32_e32 v47, v2
	v_mov_b64_e32 v[38:39], v[16:17]
	v_mov_b64_e32 v[36:37], v[14:15]
	v_mov_b64_e32 v[34:35], v[12:13]
	v_mov_b64_e32 v[32:33], v[10:11]
	v_mov_b64_e32 v[30:31], v[8:9]
	v_mov_b64_e32 v[28:29], v[6:7]
	v_mov_b64_e32 v[26:27], v[4:5]
	v_readlane_b32 s61, v245, 1
	v_readlane_b32 s62, v245, 2
	v_readlane_b32 s63, v245, 3
	v_readlane_b32 s64, v245, 4
	v_readlane_b32 s65, v245, 5
	v_readlane_b32 s69, v245, 9
	v_readlane_b32 s70, v245, 10
	v_readlane_b32 s71, v245, 11
	v_readlane_b32 s72, v245, 12
	v_readlane_b32 s73, v245, 13
	v_readlane_b32 s74, v245, 14
	v_readlane_b32 s75, v245, 15
.LBB0_982:
	s_add_i32 s8, s40, 64
	s_cmp_lt_u32 s50, 15
	s_cbranch_scc0 .Lj2_top_drain
	s_waitcnt vmcnt(8)
	s_branch .Lj2_top_go

.Lj2_top_go:
	v_cvt_pk_bf16_f32 v154, v106, v107
	v_cvt_pk_bf16_f32 v155, v108, v109
	v_cvt_pk_bf16_f32 v156, v110, v111
	v_cvt_pk_bf16_f32 v157, v112, v113
	v_add_u32_e32 v158, 0x9000, v180
	s_cmpk_gt_u32 s8, 0x103f
	s_waitcnt lgkmcnt(0)
	s_barrier
	ds_write2_b64 v180, v[134:135], v[136:137] offset1:8
	ds_write2_b64 v158, v[154:155], v[156:157] offset1:8
	s_cbranch_scc0 .LBB0_992
	s_add_i32 s8, s40, 0x80
	s_cmpk_gt_u32 s8, 0x103f
	s_cbranch_scc0 .LBB0_993

.LBB0_987:
	s_or_b64 exec, exec, s[8:9]
	s_cmp_lt_u32 s50, 16
	s_cselect_b64 s[46:47], -1, 0
	s_cmp_gt_u32 s50, 15
	s_waitcnt lgkmcnt(0)
	s_barrier
	s_cbranch_scc1 .LBB0_1002
	s_and_saveexec_b64 s[8:9], s[6:7]
	s_cbranch_execnz .LBB0_998
	s_branch .LBB0_1001
.LBB0_992:
	v_add_u32_e32 v154, 0x2000, v180
	ds_write2_b64 v154, v[140:141], v[144:145] offset0:128 offset1:136
	v_cvt_pk_bf16_f32 v154, v98, v99
	v_cvt_pk_bf16_f32 v155, v100, v101
	v_cvt_pk_bf16_f32 v156, v102, v103
	v_cvt_pk_bf16_f32 v157, v104, v105
	v_add_u32_e32 v158, 0xb000, v180
	ds_write2_b64 v158, v[154:155], v[156:157] offset0:128 offset1:136
	s_add_i32 s8, s40, 0x80
	s_cmpk_gt_u32 s8, 0x103f
	s_cbranch_scc1 .LBB0_984
.LBB0_993:
	v_add_u32_e32 v154, 0x4800, v180
	ds_write2_b64 v154, v[146:147], v[148:149] offset1:8
	v_cvt_pk_bf16_f32 v154, v114, v115
	v_cvt_pk_bf16_f32 v155, v116, v117
	v_cvt_pk_bf16_f32 v156, v118, v119
	v_cvt_pk_bf16_f32 v157, v120, v121
	v_add_u32_e32 v158, 0xd800, v180
	ds_write2_b64 v158, v[154:155], v[156:157] offset1:8
	s_add_i32 s8, s40, 0xc0
	s_cmpk_gt_u32 s8, 0x103f
	s_cbranch_scc1 .LBB0_985
.LBB0_994:
	v_add_u32_e32 v154, 0x6800, v180
	ds_write2_b64 v154, v[150:151], v[152:153] offset0:128 offset1:136
	v_cvt_pk_bf16_f32 v154, v122, v123
	v_cvt_pk_bf16_f32 v155, v124, v125
	v_cvt_pk_bf16_f32 v156, v126, v127
	v_cvt_pk_bf16_f32 v157, v128, v129
	v_add_u32_e32 v158, 0xf800, v180
	ds_write2_b64 v158, v[154:155], v[156:157] offset0:128 offset1:136
	s_and_saveexec_b64 s[8:9], s[6:7]
	s_cbranch_execnz .LBB0_986
	s_branch .LBB0_987

.LBB0_1001:
	s_or_b64 exec, exec, s[8:9]
	s_cmpk_eq_i32 s40, 0xf00
	s_cselect_b32 s58, 0xfffff000, 0
	s_cselect_b32 s61, s49, s37
	s_cselect_b32 s60, s48, s36
	s_cselect_b32 s57, -1, 0
	s_add_u32 s58, s58, s40
	s_addc_u32 s59, s57, s41
	v_lshl_add_u64 v[106:107], s[58:59], 0, v[142:143]
	v_lshlrev_b64 v[106:107], 11, v[106:107]
	v_lshl_add_u64 v[106:107], s[60:61], 0, v[106:107]
	v_lshl_add_u64 v[134:135], v[106:107], 0, v[198:199]
	global_load_dwordx4 v[106:109], v[134:135], off
	global_load_dwordx4 v[110:113], v[134:135], off offset:128
	s_add_i32 s60, s40, 0x140
	s_cmpk_gt_u32 s60, 0x103f
	s_cbranch_scc1 .Lj2_lv_done
	v_add_co_u32_e32 v102, vcc, 0x20000, v134
	s_nop 1
	v_addc_co_u32_e32 v103, vcc, 0, v135, vcc
	global_load_dwordx4 v[98:101], v[102:103], off
	s_nop 0
	global_load_dwordx4 v[102:105], v[102:103], off offset:128
	s_add_i32 s60, s40, 0x180
	s_cmpk_gt_u32 s60, 0x103f
	s_cbranch_scc1 .Lj2_lv_done
	v_add_co_u32_e32 v118, vcc, 0x40000, v134
	s_nop 1
	v_addc_co_u32_e32 v119, vcc, 0, v135, vcc
	global_load_dwordx4 v[114:117], v[118:119], off
	s_nop 0
	global_load_dwordx4 v[118:121], v[118:119], off offset:128
	s_add_i32 s60, s40, 0x1c0
	s_cmpk_gt_u32 s60, 0x103f
	s_cbranch_scc1 .Lj2_lv_done
	v_add_co_u32_e32 v126, vcc, 0x60000, v134
	s_nop 1
	v_addc_co_u32_e32 v127, vcc, 0, v135, vcc
	global_load_dwordx4 v[122:125], v[126:127], off
	s_nop 0
	global_load_dwordx4 v[126:129], v[126:127], off offset:128
.Lj2_lv_done:
.LBB0_1002:
	s_add_i32 s57, s43, s40
	s_cmpk_lt_i32 s57, 0x1040
	s_cselect_b64 s[8:9], -1, 0
	s_cmp_le_i32 s57, s51
	s_cselect_b64 s[58:59], -1, 0
	s_and_b64 s[58:59], s[8:9], s[58:59]
	v_cndmask_b32_e64 v154, 0, 1, s[58:59]
	v_cmp_ne_u32_e64 s[8:9], 1, v154
	s_andn2_b64 vcc, exec, s[58:59]
	s_cbranch_vccnz .LBB0_1008
	ds_read_b128 v[50:53], v178 offset:32
	s_cmp_le_i32 s57, s56
	s_waitcnt lgkmcnt(0)
	v_sub_f32_e32 v165, v21, v51
	v_sub_f32_e32 v164, v22, v50
	v_sub_f32_e32 v163, v23, v53
	v_sub_f32_e32 v162, v24, v52
	ds_read_b128 v[50:53], v178 offset:64
	s_waitcnt lgkmcnt(0)
	v_sub_f32_e32 v161, v25, v51
	v_sub_f32_e32 v160, v42, v50
	v_sub_f32_e32 v159, v43, v53
	v_sub_f32_e32 v158, v44, v52
	ds_read_b128 v[50:53], v177
	ds_read_b128 v[182:185], v172
	s_waitcnt lgkmcnt(0)
	v_mfma_f32_32x32x16_bf16 v[50:65], v[50:53], v[182:185], 0
	ds_read_b128 v[154:157], v177 offset:32
	ds_read_b128 v[186:189], v172 offset:1024
	s_waitcnt lgkmcnt(0)
	v_mfma_f32_32x32x16_bf16 v[50:65], v[154:157], v[186:189], v[50:65]
	ds_read_b128 v[154:157], v178 offset:96
	s_waitcnt lgkmcnt(0)
	v_sub_f32_e32 v167, v45, v155
	v_sub_f32_e32 v166, v46, v154
	v_sub_f32_e32 v171, v47, v157
	v_sub_f32_e32 v170, v48, v156
	ds_read_b128 v[154:157], v177 offset:64
	ds_read_b128 v[190:193], v172 offset:2048
	s_waitcnt lgkmcnt(0)
	v_mfma_f32_32x32x16_bf16 v[50:65], v[154:157], v[190:193], v[50:65]
	ds_read_b128 v[154:157], v178
	s_waitcnt lgkmcnt(0)
	v_sub_f32_e32 v201, v3, v157
	v_sub_f32_e32 v200, v20, v156
	v_sub_f32_e32 v169, v1, v155
	v_sub_f32_e32 v168, v2, v154
	ds_read_b128 v[154:157], v177 offset:96
	ds_read_b128 v[194:197], v172 offset:3072
	s_waitcnt lgkmcnt(0)
	v_mfma_f32_32x32x16_bf16 v[50:65], v[154:157], v[194:197], v[50:65]
	s_nop 11
	v_pk_add_f32 v[168:169], v[50:51], v[168:169]
	v_pk_add_f32 v[156:157], v[62:63], v[166:167]
	v_pk_add_f32 v[166:167], v[52:53], v[200:201]
	ds_read_b128 v[50:53], v177 offset:4608
	v_pk_add_f32 v[154:155], v[64:65], v[170:171]
	v_pk_add_f32 v[158:159], v[60:61], v[158:159]
	v_pk_add_f32 v[160:161], v[58:59], v[160:161]
	v_pk_add_f32 v[162:163], v[56:57], v[162:163]
	v_pk_add_f32 v[164:165], v[54:55], v[164:165]
	s_waitcnt lgkmcnt(0)
	v_mfma_f32_32x32x16_bf16 v[50:65], v[50:53], v[182:185], 0
	ds_read_b128 v[182:185], v177 offset:4640
	s_waitcnt lgkmcnt(0)
	v_mfma_f32_32x32x16_bf16 v[50:65], v[182:185], v[186:189], v[50:65]
	ds_read_b128 v[182:185], v177 offset:4672
	s_waitcnt lgkmcnt(0)
	v_mfma_f32_32x32x16_bf16 v[50:65], v[182:185], v[190:193], v[50:65]
	ds_read_b128 v[182:185], v177 offset:4704
	s_waitcnt lgkmcnt(0)
	v_mfma_f32_32x32x16_bf16 v[50:65], v[182:185], v[194:197], v[50:65]
	ds_read_b128 v[182:185], v178 offset:160
	s_waitcnt lgkmcnt(0)
	v_sub_f32_e32 v187, v21, v183
	v_sub_f32_e32 v186, v22, v182
	v_sub_f32_e32 v189, v23, v185
	v_sub_f32_e32 v188, v24, v184
	ds_read_b128 v[182:185], v178 offset:192
	s_nop 4
	v_pk_add_f32 v[56:57], v[56:57], v[188:189]
	v_pk_add_f32 v[54:55], v[54:55], v[186:187]
	s_waitcnt lgkmcnt(0)
	v_sub_f32_e32 v191, v25, v183
	v_sub_f32_e32 v190, v42, v182
	v_sub_f32_e32 v193, v43, v185
	v_sub_f32_e32 v192, v44, v184
	ds_read_b128 v[182:185], v178 offset:224
	v_pk_add_f32 v[60:61], v[60:61], v[192:193]
	v_pk_add_f32 v[58:59], v[58:59], v[190:191]
	s_waitcnt lgkmcnt(0)
	v_sub_f32_e32 v195, v45, v183
	v_sub_f32_e32 v194, v46, v182
	v_sub_f32_e32 v197, v47, v185
	v_sub_f32_e32 v196, v48, v184
	ds_read_b128 v[182:185], v178 offset:128
	v_pk_add_f32 v[62:63], v[62:63], v[194:195]
	s_waitcnt lgkmcnt(0)
	v_sub_f32_e32 v185, v3, v185
	v_sub_f32_e32 v184, v20, v184
	v_sub_f32_e32 v171, v1, v183
	v_sub_f32_e32 v170, v2, v182
	v_pk_add_f32 v[170:171], v[50:51], v[170:171]
	v_pk_add_f32 v[50:51], v[64:65], v[196:197]
	v_pk_add_f32 v[52:53], v[52:53], v[184:185]
	s_cbranch_scc1 .LBB0_1005
	v_add_u32_e32 v64, s40, v132
	v_add_u32_e32 v65, 32, v64
	v_cmp_le_i32_e32 vcc, v65, v175
	v_add_u32_e32 v65, 33, v64
	s_nop 0
	v_cndmask_b32_e32 v170, v219, v170, vcc
	v_cmp_lt_i32_e32 vcc, v64, v175
	s_nop 1
	v_cndmask_b32_e32 v169, v219, v169, vcc
	v_cmp_le_i32_e32 vcc, v64, v175
	s_nop 1
	v_cndmask_b32_e32 v168, v219, v168, vcc
	v_cmp_le_i32_e32 vcc, v65, v175
	v_add_u32_e32 v65, 2, v64
	s_nop 0
	v_cndmask_b32_e32 v171, v219, v171, vcc
	v_cmp_le_i32_e32 vcc, v65, v175
	v_add_u32_e32 v65, 34, v64
	s_nop 0
	v_cndmask_b32_e32 v166, v219, v166, vcc
	v_cmp_le_i32_e32 vcc, v65, v175
	v_add_u32_e32 v65, 3, v64
	s_nop 0
	v_cndmask_b32_e32 v52, v219, v52, vcc
	v_cmp_le_i32_e32 vcc, v65, v175
	v_add_u32_e32 v65, 35, v64
	s_nop 0
	v_cndmask_b32_e32 v167, v219, v167, vcc
	v_cmp_le_i32_e32 vcc, v65, v175
	v_add_u32_e32 v65, 8, v64
	s_nop 0
	v_cndmask_b32_e32 v53, v219, v53, vcc
	v_cmp_le_i32_e32 vcc, v65, v175
	v_add_u32_e32 v65, 40, v64
	s_nop 0
	v_cndmask_b32_e32 v164, v219, v164, vcc
	v_cmp_le_i32_e32 vcc, v65, v175
	v_add_u32_e32 v65, 9, v64
	s_nop 0
	v_cndmask_b32_e32 v54, v219, v54, vcc
	v_cmp_le_i32_e32 vcc, v65, v175
	v_add_u32_e32 v65, 41, v64
	s_nop 0
	v_cndmask_b32_e32 v165, v219, v165, vcc
	v_cmp_le_i32_e32 vcc, v65, v175
	v_add_u32_e32 v65, 10, v64
	s_nop 0
	v_cndmask_b32_e32 v55, v219, v55, vcc
	v_cmp_le_i32_e32 vcc, v65, v175
	v_add_u32_e32 v65, 42, v64
	s_nop 0
	v_cndmask_b32_e32 v162, v219, v162, vcc
	v_cmp_le_i32_e32 vcc, v65, v175
	v_add_u32_e32 v65, 11, v64
	s_nop 0
	v_cndmask_b32_e32 v56, v219, v56, vcc
	v_cmp_le_i32_e32 vcc, v65, v175
	v_add_u32_e32 v65, 43, v64
	s_nop 0
	v_cndmask_b32_e32 v163, v219, v163, vcc
	v_cmp_le_i32_e32 vcc, v65, v175
	v_add_u32_e32 v65, 16, v64
	s_nop 0
	v_cndmask_b32_e32 v57, v219, v57, vcc
	v_cmp_le_i32_e32 vcc, v65, v175
	v_add_u32_e32 v65, 48, v64
	s_nop 0
	v_cndmask_b32_e32 v160, v219, v160, vcc
	v_cmp_le_i32_e32 vcc, v65, v175
	v_add_u32_e32 v65, 17, v64
	s_nop 0
	v_cndmask_b32_e32 v58, v219, v58, vcc
	v_cmp_le_i32_e32 vcc, v65, v175
	v_add_u32_e32 v65, 49, v64
	s_nop 0
	v_cndmask_b32_e32 v161, v219, v161, vcc
	v_cmp_le_i32_e32 vcc, v65, v175
	v_add_u32_e32 v65, 18, v64
	s_nop 0
	v_cndmask_b32_e32 v59, v219, v59, vcc
	v_cmp_le_i32_e32 vcc, v65, v175
	v_add_u32_e32 v65, 50, v64
	s_nop 0
	v_cndmask_b32_e32 v158, v219, v158, vcc
	v_cmp_le_i32_e32 vcc, v65, v175
	v_add_u32_e32 v65, 19, v64
	s_nop 0
	v_cndmask_b32_e32 v60, v219, v60, vcc
	v_cmp_le_i32_e32 vcc, v65, v175
	v_add_u32_e32 v65, 51, v64
	s_nop 0
	v_cndmask_b32_e32 v159, v219, v159, vcc
	v_cmp_le_i32_e32 vcc, v65, v175
	v_add_u32_e32 v65, 24, v64
	s_nop 0
	v_cndmask_b32_e32 v61, v219, v61, vcc
	v_cmp_le_i32_e32 vcc, v65, v175
	v_add_u32_e32 v65, 56, v64
	s_nop 0
	v_cndmask_b32_e32 v156, v219, v156, vcc
	v_cmp_le_i32_e32 vcc, v65, v175
	v_add_u32_e32 v65, 25, v64
	s_nop 0
	v_cndmask_b32_e32 v62, v219, v62, vcc
	v_cmp_le_i32_e32 vcc, v65, v175
	v_add_u32_e32 v65, 57, v64
	s_nop 0
	v_cndmask_b32_e32 v157, v219, v157, vcc
	v_cmp_le_i32_e32 vcc, v65, v175
	v_add_u32_e32 v65, 26, v64
	s_nop 0
	v_cndmask_b32_e32 v63, v219, v63, vcc
	v_cmp_le_i32_e32 vcc, v65, v175
	v_add_u32_e32 v65, 58, v64
	s_nop 0
	v_cndmask_b32_e32 v154, v219, v154, vcc
	v_cmp_le_i32_e32 vcc, v65, v175
	v_add_u32_e32 v65, 27, v64
	v_add_u32_e32 v64, 59, v64
	v_cndmask_b32_e32 v50, v219, v50, vcc
	v_cmp_le_i32_e32 vcc, v65, v175
	s_nop 1
	v_cndmask_b32_e32 v155, v219, v155, vcc
	v_cmp_le_i32_e32 vcc, v64, v175
	s_nop 1
	v_cndmask_b32_e32 v51, v219, v51, vcc

.LBB0_1009:
	s_andn2_b64 vcc, exec, s[46:47]
	s_cbranch_vccnz .LBB0_1015
	s_cmp_lt_u32 s50, 15
	s_cbranch_scc0 .Lj2_ck_drain
	s_waitcnt vmcnt(8)
	s_branch .Lj2_ck_go

.Lj2_ck_go:
	v_cvt_pk_bf16_f32 v134, v74, v75
	v_cvt_pk_bf16_f32 v135, v76, v77
	v_cvt_pk_bf16_f32 v136, v78, v79
	v_cvt_pk_bf16_f32 v137, v80, v81
	v_cvt_pk_bf16_f32 v140, v66, v67
	v_cvt_pk_bf16_f32 v141, v68, v69
	v_cvt_pk_bf16_f32 v144, v70, v71
	v_cvt_pk_bf16_f32 v145, v72, v73
	v_cvt_pk_bf16_f32 v146, v82, v83
	v_cvt_pk_bf16_f32 v147, v84, v85
	v_cvt_pk_bf16_f32 v148, v86, v87
	v_cvt_pk_bf16_f32 v149, v88, v89
	v_cvt_pk_bf16_f32 v150, v90, v91
	v_cvt_pk_bf16_f32 v151, v92, v93
	v_cvt_pk_bf16_f32 v152, v94, v95
	v_cvt_pk_bf16_f32 v153, v96, v97
	s_cmp_gt_u32 s50, 14
	s_cbranch_scc1 .LBB0_1015
	s_cmpk_eq_i32 s40, 0xe00
	s_cselect_b32 s58, 0xfffff000, 0
	s_cselect_b32 s61, s45, s13
	s_cselect_b32 s60, s44, s12
	s_cselect_b32 s57, -1, 0
	s_add_u32 s58, s58, s40
	s_addc_u32 s59, s57, s41
	s_add_u32 s58, s58, 0x100
	s_addc_u32 s59, s59, 0
	v_lshl_add_u64 v[74:75], s[58:59], 0, v[142:143]
	v_lshlrev_b64 v[74:75], 11, v[74:75]
	v_lshl_add_u64 v[74:75], s[60:61], 0, v[74:75]
	v_lshl_add_u64 v[154:155], v[74:75], 0, v[198:199]
	global_load_dwordx4 v[74:77], v[154:155], off
	global_load_dwordx4 v[78:81], v[154:155], off offset:128
	s_add_i32 s60, s40, 0x240
	s_cmpk_gt_u32 s60, 0x103f
	s_cbranch_scc1 .LBB0_1015
	v_add_co_u32_e32 v70, vcc, 0x20000, v154
	s_nop 1
	v_addc_co_u32_e32 v71, vcc, 0, v155, vcc
	global_load_dwordx4 v[66:69], v[70:71], off
	s_nop 0
	global_load_dwordx4 v[70:73], v[70:71], off offset:128
	s_add_i32 s60, s40, 0x280
	s_cmpk_gt_u32 s60, 0x103f
	s_cbranch_scc1 .LBB0_1015
	v_add_co_u32_e32 v86, vcc, 0x40000, v154
	s_nop 1
	v_addc_co_u32_e32 v87, vcc, 0, v155, vcc
	global_load_dwordx4 v[82:85], v[86:87], off
	s_nop 0
	global_load_dwordx4 v[86:89], v[86:87], off offset:128
	s_add_i32 s60, s40, 0x2c0
	s_cmpk_gt_u32 s60, 0x103f
	s_cbranch_scc1 .LBB0_1015
	v_add_co_u32_e32 v94, vcc, 0x60000, v154
	s_nop 1
	v_addc_co_u32_e32 v95, vcc, 0, v155, vcc
	global_load_dwordx4 v[90:93], v[94:95], off
	s_nop 0
	global_load_dwordx4 v[94:97], v[94:95], off offset:128

.LBB0_1017:
	s_add_u32 s40, s40, 0x100
	s_addc_u32 s41, s41, 0
	s_add_i32 s50, s50, 1
	s_cmpk_eq_i32 s40, 0x1100
	s_cbranch_scc1 .LBB0_1021
	v_mov_b32_e32 v181, v182
	s_branch .LBB0_982
.LBB0_1021:
	v_and_b32_e32 v2, 64, v218
	v_xor_b32_e32 v1, 32, v218
	v_add_u32_e32 v2, 64, v2
	v_cmp_lt_i32_e32 vcc, v1, v2
	s_lshl_b32 s6, s38, 13
	s_add_i32 s6, s6, 0
	v_cndmask_b32_e32 v1, v218, v1, vcc
	v_lshlrev_b32_e32 v1, 2, v1
	ds_bpermute_b32 v1, v1, v173
	v_lshl_add_u32 v2, v139, 2, s6
	v_cmp_gt_u32_e32 vcc, 32, v139
	s_waitcnt lgkmcnt(0)
	s_barrier
	ds_write2st64_b32 v2, v4, v5 offset1:1
	ds_write2st64_b32 v2, v26, v27 offset0:16 offset1:17
	ds_write2st64_b32 v2, v6, v7 offset0:2 offset1:3
	ds_write2st64_b32 v2, v28, v29 offset0:18 offset1:19
	ds_write2st64_b32 v2, v8, v9 offset0:4 offset1:5
	ds_write2st64_b32 v2, v30, v31 offset0:20 offset1:21
	ds_write2st64_b32 v2, v10, v11 offset0:6 offset1:7
	ds_write2st64_b32 v2, v32, v33 offset0:22 offset1:23
	ds_write2st64_b32 v2, v12, v13 offset0:8 offset1:9
	ds_write2st64_b32 v2, v34, v35 offset0:24 offset1:25
	ds_write2st64_b32 v2, v14, v15 offset0:10 offset1:11
	ds_write2st64_b32 v2, v36, v37 offset0:26 offset1:27
	ds_write2st64_b32 v2, v16, v17 offset0:12 offset1:13
	ds_write2st64_b32 v2, v38, v39 offset0:28 offset1:29
	ds_write2st64_b32 v2, v18, v19 offset0:14 offset1:15
	ds_write2st64_b32 v2, v40, v41 offset0:30 offset1:31
	s_and_saveexec_b64 s[6:7], vcc
	s_cbranch_execz .LBB0_1023
	s_lshl_b32 s8, s38, 7
	s_add_i32 s8, s8, 0
	v_lshl_add_u32 v2, v133, 2, s8
	v_add_u32_e32 v3, 0x10400, v2
	v_add_u32_e32 v2, 0x10000, v2
	v_add_f32_e32 v1, v173, v1
	ds_write_b32 v2, v182
	ds_write_b32 v3, v1

.LBB0_1421:
	v_lshl_add_u32 v122, s60, 8, v1
	v_ashrrev_i32_e32 v123, 31, v122
	s_lshl_b32 s27, s62, 8
	v_lshl_add_u64 v[124:125], v[122:123], 2, s[22:23]
	v_add_u32_e32 v126, 0x80, v122
	v_add_u32_e32 v128, 0x90, v122
	v_add_u32_e32 v130, 0xa0, v122
	v_add_u32_e32 v122, 0xb0, v122
	s_or_b32 s27, s27, s75
	v_ashrrev_i32_e32 v127, 31, v126
	v_ashrrev_i32_e32 v129, 31, v128
	v_ashrrev_i32_e32 v131, 31, v130
	v_ashrrev_i32_e32 v123, 31, v122
	s_ashr_i32 s27, s27, 1
	global_load_dword v194, v[124:125], off
	v_lshl_add_u64 v[126:127], v[126:127], 2, s[22:23]
	v_lshl_add_u64 v[128:129], v[128:129], 2, s[22:23]
	v_lshl_add_u64 v[130:131], v[130:131], 2, s[22:23]
	v_lshl_add_u64 v[122:123], v[122:123], 2, s[22:23]
	global_load_dword v192, v[124:125], off offset:64
	global_load_dword v190, v[124:125], off offset:128
	global_load_dword v188, v[124:125], off offset:192
	global_load_dword v186, v[126:127], off
	global_load_dword v182, v[128:129], off
	global_load_dword v180, v[130:131], off
	global_load_dword v178, v[122:123], off
	v_or_b32_e32 v184, s27, v217
	v_ashrrev_i32_e32 v185, 31, v184
	v_readlane_b32 s36, v245, 19
	v_lshlrev_b64 v[134:135], 2, v[184:185]
	v_readlane_b32 s42, v245, 25
	v_readlane_b32 s43, v245, 26
	v_readlane_b32 s44, v245, 27
	v_readlane_b32 s45, v245, 28
	v_lshl_add_u64 v[196:197], s[42:43], 0, v[134:135]
	v_lshl_add_u64 v[122:123], s[30:31], 0, v[134:135]
	v_lshl_add_u64 v[124:125], s[88:89], 0, v[134:135]
	global_load_dwordx4 v[146:149], v[196:197], off
	global_load_dwordx4 v[142:145], v[122:123], off
	global_load_dwordx4 v[138:141], v[124:125], off
	v_lshl_add_u64 v[198:199], s[44:45], 0, v[134:135]
	v_lshl_add_u64 v[122:123], s[90:91], 0, v[134:135]
	v_lshl_add_u64 v[124:125], s[92:93], 0, v[134:135]
	v_lshl_add_u64 v[126:127], s[94:95], 0, v[134:135]
	v_lshl_add_u64 v[134:135], s[52:53], 0, v[134:135]
	global_load_dwordx4 v[150:153], v[198:199], off
	global_load_dwordx4 v[130:133], v[122:123], off
	s_nop 0
	global_load_dwordx4 v[122:125], v[124:125], off
	s_lshl_b32 s27, s60, 2
	global_load_dwordx4 v[126:129], v[126:127], off
	global_load_dwordx4 v[134:137], v[134:135], off
	s_add_i32 s60, s27, s33
	v_lshl_or_b32 v179, s60, 6, v166
	v_readlane_b32 s37, v245, 20
	v_readlane_b32 s38, v245, 21
	v_readlane_b32 s39, v245, 22
	v_readlane_b32 s40, v245, 23
	v_readlane_b32 s41, v245, 24
	v_readlane_b32 s46, v245, 29
	v_readlane_b32 s47, v245, 30
	v_readlane_b32 s48, v245, 31
	v_readlane_b32 s49, v245, 32
	v_readlane_b32 s50, v245, 33
	v_readlane_b32 s51, v245, 34
	s_waitcnt vmcnt(0)
	v_pk_mul_f32 v[160:161], v[160:161], v[194:195] op_sel_hi:[1,0]
	v_pk_mul_f32 v[158:159], v[158:159], v[194:195] op_sel_hi:[1,0]
	v_pk_mul_f32 v[156:157], v[156:157], v[194:195] op_sel_hi:[1,0]
	v_pk_mul_f32 v[154:155], v[154:155], v[194:195] op_sel_hi:[1,0]
	v_mov_b32_dpp v204, v158 row_ror:1 row_mask:0xf bank_mask:0xf
	v_mov_b32_dpp v205, v159 row_ror:1 row_mask:0xf bank_mask:0xf
	v_mov_b32_dpp v206, v160 row_ror:1 row_mask:0xf bank_mask:0xf
	v_mov_b32_dpp v207, v161 row_ror:1 row_mask:0xf bank_mask:0xf
	v_mov_b32_dpp v208, v158 row_ror:2 row_mask:0xf bank_mask:0xf
	v_mov_b32_dpp v209, v159 row_ror:2 row_mask:0xf bank_mask:0xf
	v_mov_b32_dpp v210, v160 row_ror:2 row_mask:0xf bank_mask:0xf
	v_mov_b32_dpp v211, v161 row_ror:2 row_mask:0xf bank_mask:0xf
	v_mov_b32_dpp v200, v154 row_ror:1 row_mask:0xf bank_mask:0xf
	v_mov_b32_dpp v201, v155 row_ror:1 row_mask:0xf bank_mask:0xf
	v_mov_b32_dpp v202, v156 row_ror:1 row_mask:0xf bank_mask:0xf
	v_mov_b32_dpp v203, v157 row_ror:1 row_mask:0xf bank_mask:0xf
	v_mov_b32_dpp v212, v154 row_ror:2 row_mask:0xf bank_mask:0xf
	v_mov_b32_dpp v213, v155 row_ror:2 row_mask:0xf bank_mask:0xf
	v_mov_b32_dpp v214, v156 row_ror:2 row_mask:0xf bank_mask:0xf
	v_mov_b32_dpp v215, v157 row_ror:2 row_mask:0xf bank_mask:0xf
	v_mov_b32_dpp v204, v158 row_shr:1 row_mask:0xf bank_mask:0xf
	v_mov_b32_dpp v205, v159 row_shr:1 row_mask:0xf bank_mask:0xf
	v_mov_b32_dpp v206, v160 row_shr:1 row_mask:0xf bank_mask:0xf
	v_mov_b32_dpp v207, v161 row_shr:1 row_mask:0xf bank_mask:0xf
	v_mov_b32_dpp v208, v158 row_shr:2 row_mask:0xf bank_mask:0xf
	v_mov_b32_dpp v209, v159 row_shr:2 row_mask:0xf bank_mask:0xf
	v_mov_b32_dpp v210, v160 row_shr:2 row_mask:0xf bank_mask:0xf
	v_mov_b32_dpp v211, v161 row_shr:2 row_mask:0xf bank_mask:0xf
	v_mov_b32_dpp v200, v154 row_shr:1 row_mask:0xf bank_mask:0xf
	v_mov_b32_dpp v201, v155 row_shr:1 row_mask:0xf bank_mask:0xf
	v_mov_b32_dpp v202, v156 row_shr:1 row_mask:0xf bank_mask:0xf
	v_mov_b32_dpp v203, v157 row_shr:1 row_mask:0xf bank_mask:0xf
	v_mov_b32_dpp v212, v154 row_shr:2 row_mask:0xf bank_mask:0xf
	v_mov_b32_dpp v213, v155 row_shr:2 row_mask:0xf bank_mask:0xf
	v_mov_b32_dpp v214, v156 row_shr:2 row_mask:0xf bank_mask:0xf
	v_mov_b32_dpp v215, v157 row_shr:2 row_mask:0xf bank_mask:0xf
	s_and_saveexec_b64 s[62:63], s[6:7]
	s_cbranch_execz .LBB0_1423
	v_pk_fma_f32 v[210:211], v[148:149], v[210:211], v[152:153]
	v_pk_fma_f32 v[208:209], v[146:147], v[208:209], v[150:151]
	v_pk_fma_f32 v[206:207], v[144:145], v[206:207], v[210:211]
	v_pk_fma_f32 v[204:205], v[142:143], v[204:205], v[208:209]
	v_pk_fma_f32 v[206:207], v[160:161], v[140:141], v[206:207]
	v_pk_fma_f32 v[204:205], v[158:159], v[138:139], v[204:205]
	v_mul_f32_e32 v181, 0xbfb8aa3b, v207
	v_exp_f32_e32 v181, v181
	v_mul_f32_e32 v183, 0xbfb8aa3b, v206
	v_exp_f32_e32 v183, v183
	v_mul_f32_e32 v187, 0xbfb8aa3b, v204
	v_add_f32_e32 v181, 1.0, v181
	v_rcp_f32_e32 v209, v181
	v_add_f32_e32 v181, 1.0, v183
	v_mul_f32_e32 v183, 0xbfb8aa3b, v205
	v_exp_f32_e32 v183, v183
	v_exp_f32_e32 v187, v187
	v_rcp_f32_e32 v208, v181
	v_pk_fma_f32 v[212:213], v[130:131], v[212:213], v[134:135]
	v_add_f32_e32 v181, 1.0, v183
	v_rcp_f32_e32 v211, v181
	v_add_f32_e32 v181, 1.0, v187
	v_rcp_f32_e32 v210, v181
	v_pk_fma_f32 v[214:215], v[132:133], v[214:215], v[136:137]
	v_pk_fma_f32 v[200:201], v[122:123], v[200:201], v[212:213]
	v_pk_fma_f32 v[202:203], v[124:125], v[202:203], v[214:215]
	v_pk_fma_f32 v[200:201], v[154:155], v[126:127], v[200:201]
	v_pk_mul_f32 v[204:205], v[204:205], v[210:211]
	v_pk_fma_f32 v[202:203], v[156:157], v[128:129], v[202:203]
	v_pk_mul_f32 v[200:201], v[204:205], v[200:201]
	v_pk_mul_f32 v[204:205], v[206:207], v[208:209]
	v_cvt_pk_bf16_f32 v200, v200, v201
	v_pk_mul_f32 v[202:203], v[204:205], v[202:203]
	v_mov_b64_e32 v[204:205], s[18:19]
	v_mad_i64_i32 v[204:205], s[42:43], v179, s82, v[204:205]
	v_lshl_add_u64 v[204:205], v[184:185], 1, v[204:205]
	v_cvt_pk_bf16_f32 v201, v202, v203
	global_store_dwordx2 v[204:205], v[200:201], off

.LBB0_1425:
	s_or_b64 exec, exec, s[64:65]
	v_lshl_add_u64 v[206:207], s[62:63], 0, v[168:169]
	v_mad_u64_u32 v[204:205], s[42:43], v206, s83, 0
	v_mad_i32_i24 v205, v207, s83, v205
	v_pk_mul_f32 v[206:207], v[120:121], v[192:193] op_sel_hi:[1,0]
	v_pk_mul_f32 v[210:211], v[114:115], v[192:193] op_sel_hi:[1,0]
	v_pk_mul_f32 v[208:209], v[116:117], v[192:193] op_sel_hi:[1,0]
	v_mov_b32_dpp v114, v158 row_ror:1 row_mask:0xf bank_mask:0xf
	v_mov_b32_dpp v115, v159 row_ror:1 row_mask:0xf bank_mask:0xf
	v_mov_b32_dpp v120, v158 row_ror:2 row_mask:0xf bank_mask:0xf
	v_mov_b32_dpp v121, v159 row_ror:2 row_mask:0xf bank_mask:0xf
	v_mov_b32_dpp v116, v160 row_ror:1 row_mask:0xf bank_mask:0xf
	v_mov_b32_dpp v117, v161 row_ror:1 row_mask:0xf bank_mask:0xf
	v_mov_b32_dpp v158, v160 row_ror:2 row_mask:0xf bank_mask:0xf
	v_mov_b32_dpp v159, v161 row_ror:2 row_mask:0xf bank_mask:0xf
	s_nop 0
	v_mov_b32_dpp v158, v206 row_shr:2 row_mask:0xf bank_mask:0xf
	v_mov_b32_dpp v159, v207 row_shr:2 row_mask:0xf bank_mask:0xf
	v_mov_b32_dpp v160, v154 row_ror:1 row_mask:0xf bank_mask:0xf
	v_mov_b32_dpp v161, v155 row_ror:1 row_mask:0xf bank_mask:0xf
	v_mov_b32_dpp v214, v154 row_ror:2 row_mask:0xf bank_mask:0xf
	v_mov_b32_dpp v215, v155 row_ror:2 row_mask:0xf bank_mask:0xf
	v_pk_mul_f32 v[118:119], v[118:119], v[192:193] op_sel_hi:[1,0]
	v_mov_b32_dpp v116, v206 row_shr:1 row_mask:0xf bank_mask:0xf
	v_mov_b32_dpp v117, v207 row_shr:1 row_mask:0xf bank_mask:0xf
	v_mov_b32_dpp v212, v156 row_ror:1 row_mask:0xf bank_mask:0xf
	v_mov_b32_dpp v213, v157 row_ror:1 row_mask:0xf bank_mask:0xf
	v_mov_b32_dpp v154, v156 row_ror:2 row_mask:0xf bank_mask:0xf
	v_mov_b32_dpp v155, v157 row_ror:2 row_mask:0xf bank_mask:0xf
	v_pk_fma_f32 v[156:157], v[148:149], v[158:159], v[152:153]
	v_mov_b32_dpp v120, v118 row_shr:2 row_mask:0xf bank_mask:0xf
	v_mov_b32_dpp v121, v119 row_shr:2 row_mask:0xf bank_mask:0xf
	v_pk_fma_f32 v[116:117], v[144:145], v[116:117], v[156:157]
	v_mov_b32_dpp v114, v118 row_shr:1 row_mask:0xf bank_mask:0xf
	v_mov_b32_dpp v115, v119 row_shr:1 row_mask:0xf bank_mask:0xf
	v_pk_fma_f32 v[120:121], v[146:147], v[120:121], v[150:151]
	v_pk_fma_f32 v[116:117], v[206:207], v[140:141], v[116:117]
	v_pk_fma_f32 v[114:115], v[142:143], v[114:115], v[120:121]
	v_mul_f32_e32 v120, 0xbfb8aa3b, v117
	v_exp_f32_e32 v120, v120
	v_mul_f32_e32 v121, 0xbfb8aa3b, v116
	v_exp_f32_e32 v156, v121
	v_pk_fma_f32 v[114:115], v[118:119], v[138:139], v[114:115]
	v_add_f32_e32 v120, 1.0, v120
	v_rcp_f32_e32 v121, v120
	v_add_f32_e32 v120, 1.0, v156
	v_mul_f32_e32 v156, 0xbfb8aa3b, v115
	v_exp_f32_e32 v156, v156
	v_mul_f32_e32 v157, 0xbfb8aa3b, v114
	v_exp_f32_e32 v158, v157
	v_mov_b32_dpp v214, v210 row_shr:2 row_mask:0xf bank_mask:0xf
	v_add_f32_e32 v156, 1.0, v156
	v_rcp_f32_e32 v157, v156
	v_add_f32_e32 v156, 1.0, v158
	v_rcp_f32_e32 v156, v156
	v_mov_b32_dpp v215, v211 row_shr:2 row_mask:0xf bank_mask:0xf
	v_rcp_f32_e32 v120, v120
	v_mov_b32_dpp v160, v210 row_shr:1 row_mask:0xf bank_mask:0xf
	v_mov_b32_dpp v161, v211 row_shr:1 row_mask:0xf bank_mask:0xf
	v_mov_b32_dpp v154, v208 row_shr:2 row_mask:0xf bank_mask:0xf
	v_mov_b32_dpp v155, v209 row_shr:2 row_mask:0xf bank_mask:0xf
	v_pk_fma_f32 v[158:159], v[130:131], v[214:215], v[134:135]
	v_mov_b32_dpp v212, v208 row_shr:1 row_mask:0xf bank_mask:0xf
	v_mov_b32_dpp v213, v209 row_shr:1 row_mask:0xf bank_mask:0xf
	v_pk_fma_f32 v[154:155], v[132:133], v[154:155], v[136:137]
	v_pk_fma_f32 v[158:159], v[122:123], v[160:161], v[158:159]
	v_pk_fma_f32 v[154:155], v[124:125], v[212:213], v[154:155]
	v_pk_fma_f32 v[158:159], v[210:211], v[126:127], v[158:159]
	v_pk_mul_f32 v[114:115], v[114:115], v[156:157]
	v_pk_fma_f32 v[154:155], v[208:209], v[128:129], v[154:155]
	v_pk_mul_f32 v[156:157], v[114:115], v[158:159]
	v_pk_mul_f32 v[114:115], v[116:117], v[120:121]
	v_mov_b64_e32 v[116:117], s[18:19]
	v_pk_mul_f32 v[154:155], v[114:115], v[154:155]
	v_or_b32_e32 v114, 16, v179
	v_mad_i64_i32 v[114:115], s[42:43], v114, s82, v[116:117]
	v_lshlrev_b64 v[120:121], 1, v[184:185]
	v_cvt_pk_bf16_f32 v156, v156, v157
	v_cvt_pk_bf16_f32 v157, v154, v155
	v_pk_mul_f32 v[154:155], v[110:111], v[190:191] op_sel_hi:[1,0]
	v_lshl_add_u64 v[114:115], v[114:115], 0, v[120:121]
	v_mov_b32_dpp v110, v118 row_ror:1 row_mask:0xf bank_mask:0xf
	v_mov_b32_dpp v111, v119 row_ror:1 row_mask:0xf bank_mask:0xf
	v_mov_b32_dpp v158, v118 row_ror:2 row_mask:0xf bank_mask:0xf
	v_mov_b32_dpp v159, v119 row_ror:2 row_mask:0xf bank_mask:0xf
	global_store_dwordx2 v[114:115], v[156:157], off
	v_pk_mul_f32 v[112:113], v[112:113], v[190:191] op_sel_hi:[1,0]
	v_mov_b32_dpp v118, v206 row_ror:2 row_mask:0xf bank_mask:0xf
	v_mov_b32_dpp v119, v207 row_ror:2 row_mask:0xf bank_mask:0xf
	v_mov_b32_dpp v156, v206 row_ror:1 row_mask:0xf bank_mask:0xf
	v_mov_b32_dpp v157, v207 row_ror:1 row_mask:0xf bank_mask:0xf
	v_mov_b32_dpp v118, v112 row_shr:2 row_mask:0xf bank_mask:0xf
	v_mov_b32_dpp v119, v113 row_shr:2 row_mask:0xf bank_mask:0xf
	v_mov_b32_dpp v156, v112 row_shr:1 row_mask:0xf bank_mask:0xf
	v_mov_b32_dpp v157, v113 row_shr:1 row_mask:0xf bank_mask:0xf
	v_pk_fma_f32 v[118:119], v[148:149], v[118:119], v[152:153]
	v_mov_b32_dpp v158, v154 row_shr:2 row_mask:0xf bank_mask:0xf
	v_pk_fma_f32 v[118:119], v[144:145], v[156:157], v[118:119]
	v_mov_b32_dpp v159, v155 row_shr:2 row_mask:0xf bank_mask:0xf
	v_pk_fma_f32 v[118:119], v[112:113], v[140:141], v[118:119]
	v_mov_b32_dpp v110, v154 row_shr:1 row_mask:0xf bank_mask:0xf
	v_mul_f32_e32 v156, 0xbfb8aa3b, v119
	v_mov_b32_dpp v111, v155 row_shr:1 row_mask:0xf bank_mask:0xf
	v_pk_fma_f32 v[158:159], v[146:147], v[158:159], v[150:151]
	v_exp_f32_e32 v156, v156
	v_mul_f32_e32 v157, 0xbfb8aa3b, v118
	v_pk_fma_f32 v[110:111], v[142:143], v[110:111], v[158:159]
	v_exp_f32_e32 v158, v157
	v_pk_fma_f32 v[110:111], v[154:155], v[138:139], v[110:111]
	v_add_f32_e32 v156, 1.0, v156
	v_rcp_f32_e32 v157, v156
	v_add_f32_e32 v156, 1.0, v158
	v_mul_f32_e32 v158, 0xbfb8aa3b, v111
	v_exp_f32_e32 v158, v158
	v_mul_f32_e32 v159, 0xbfb8aa3b, v110
	v_exp_f32_e32 v181, v159
	v_add_f32_e32 v158, 1.0, v158
	v_mov_b32_dpp v160, v210 row_ror:1 row_mask:0xf bank_mask:0xf
	v_mov_b32_dpp v161, v211 row_ror:1 row_mask:0xf bank_mask:0xf
	v_mov_b32_dpp v212, v210 row_ror:2 row_mask:0xf bank_mask:0xf
	v_mov_b32_dpp v213, v211 row_ror:2 row_mask:0xf bank_mask:0xf
	v_rcp_f32_e32 v159, v158
	v_add_f32_e32 v158, 1.0, v181
	v_pk_mul_f32 v[108:109], v[108:109], v[190:191] op_sel_hi:[1,0]
	v_pk_mul_f32 v[106:107], v[106:107], v[190:191] op_sel_hi:[1,0]
	v_mov_b32_dpp v210, v208 row_ror:2 row_mask:0xf bank_mask:0xf
	v_mov_b32_dpp v211, v209 row_ror:2 row_mask:0xf bank_mask:0xf
	v_rcp_f32_e32 v158, v158
	v_mov_b32_dpp v212, v106 row_shr:2 row_mask:0xf bank_mask:0xf
	v_mov_b32_dpp v213, v107 row_shr:2 row_mask:0xf bank_mask:0xf
	v_mov_b32_dpp v210, v108 row_shr:2 row_mask:0xf bank_mask:0xf
	v_mov_b32_dpp v211, v109 row_shr:2 row_mask:0xf bank_mask:0xf
	v_rcp_f32_e32 v156, v156
	v_mov_b32_dpp v160, v106 row_shr:1 row_mask:0xf bank_mask:0xf
	v_mov_b32_dpp v161, v107 row_shr:1 row_mask:0xf bank_mask:0xf
	v_mov_b32_dpp v206, v208 row_ror:1 row_mask:0xf bank_mask:0xf
	v_mov_b32_dpp v207, v209 row_ror:1 row_mask:0xf bank_mask:0xf
	v_pk_fma_f32 v[208:209], v[132:133], v[210:211], v[136:137]
	v_pk_fma_f32 v[210:211], v[130:131], v[212:213], v[134:135]
	v_mov_b32_dpp v206, v108 row_shr:1 row_mask:0xf bank_mask:0xf
	v_mov_b32_dpp v207, v109 row_shr:1 row_mask:0xf bank_mask:0xf
	v_pk_fma_f32 v[160:161], v[122:123], v[160:161], v[210:211]
	v_pk_fma_f32 v[206:207], v[124:125], v[206:207], v[208:209]
	v_pk_fma_f32 v[160:161], v[106:107], v[126:127], v[160:161]
	v_pk_mul_f32 v[110:111], v[110:111], v[158:159]
	v_pk_fma_f32 v[206:207], v[108:109], v[128:129], v[206:207]
	v_pk_mul_f32 v[158:159], v[110:111], v[160:161]
	v_pk_mul_f32 v[110:111], v[118:119], v[156:157]
	v_cvt_pk_bf16_f32 v156, v158, v159
	v_pk_mul_f32 v[118:119], v[110:111], v[206:207]
	v_or_b32_e32 v110, 32, v179
	v_mad_i64_i32 v[110:111], s[42:43], v110, s82, v[116:117]
	v_cvt_pk_bf16_f32 v157, v118, v119
	v_lshl_add_u64 v[110:111], v[110:111], 0, v[120:121]
	v_mov_b32_dpp v118, v154 row_ror:1 row_mask:0xf bank_mask:0xf
	v_mov_b32_dpp v119, v155 row_ror:1 row_mask:0xf bank_mask:0xf
	v_mov_b32_dpp v158, v154 row_ror:2 row_mask:0xf bank_mask:0xf
	v_mov_b32_dpp v159, v155 row_ror:2 row_mask:0xf bank_mask:0xf
	global_store_dwordx2 v[110:111], v[156:157], off
	v_pk_mul_f32 v[104:105], v[104:105], v[188:189] op_sel_hi:[1,0]
	v_mov_b32_dpp v154, v112 row_ror:2 row_mask:0xf bank_mask:0xf
	v_mov_b32_dpp v155, v113 row_ror:2 row_mask:0xf bank_mask:0xf
	v_pk_mul_f32 v[102:103], v[102:103], v[188:189] op_sel_hi:[1,0]
	v_mov_b32_dpp v156, v112 row_ror:1 row_mask:0xf bank_mask:0xf
	v_mov_b32_dpp v157, v113 row_ror:1 row_mask:0xf bank_mask:0xf
	v_mov_b32_dpp v154, v104 row_shr:2 row_mask:0xf bank_mask:0xf
	v_mov_b32_dpp v155, v105 row_shr:2 row_mask:0xf bank_mask:0xf
	v_mov_b32_dpp v156, v104 row_shr:1 row_mask:0xf bank_mask:0xf
	v_mov_b32_dpp v157, v105 row_shr:1 row_mask:0xf bank_mask:0xf
	v_mov_b32_dpp v158, v102 row_shr:2 row_mask:0xf bank_mask:0xf
	v_mov_b32_dpp v159, v103 row_shr:2 row_mask:0xf bank_mask:0xf
	v_mov_b32_dpp v112, v106 row_ror:1 row_mask:0xf bank_mask:0xf
	v_mov_b32_dpp v113, v107 row_ror:1 row_mask:0xf bank_mask:0xf
	v_mov_b32_dpp v206, v106 row_ror:2 row_mask:0xf bank_mask:0xf
	v_mov_b32_dpp v207, v107 row_ror:2 row_mask:0xf bank_mask:0xf
	v_pk_fma_f32 v[154:155], v[148:149], v[154:155], v[152:153]
	v_mov_b32_dpp v118, v102 row_shr:1 row_mask:0xf bank_mask:0xf
	v_mov_b32_dpp v119, v103 row_shr:1 row_mask:0xf bank_mask:0xf
	v_mov_b32_dpp v160, v108 row_ror:1 row_mask:0xf bank_mask:0xf
	v_mov_b32_dpp v161, v109 row_ror:1 row_mask:0xf bank_mask:0xf
	v_mov_b32_dpp v106, v108 row_ror:2 row_mask:0xf bank_mask:0xf
	v_mov_b32_dpp v107, v109 row_ror:2 row_mask:0xf bank_mask:0xf
	v_pk_fma_f32 v[108:109], v[146:147], v[158:159], v[150:151]
	v_pk_fma_f32 v[154:155], v[144:145], v[156:157], v[154:155]
	v_pk_fma_f32 v[108:109], v[142:143], v[118:119], v[108:109]
	v_pk_fma_f32 v[118:119], v[104:105], v[140:141], v[154:155]
	v_pk_fma_f32 v[108:109], v[102:103], v[138:139], v[108:109]
	v_mul_f32_e32 v154, 0xbfb8aa3b, v119
	v_exp_f32_e32 v154, v154
	v_mul_f32_e32 v155, 0xbfb8aa3b, v118
	v_exp_f32_e32 v156, v155
	v_mul_f32_e32 v157, 0xbfb8aa3b, v108
	v_add_f32_e32 v154, 1.0, v154
	v_rcp_f32_e32 v155, v154
	v_add_f32_e32 v154, 1.0, v156
	v_mul_f32_e32 v156, 0xbfb8aa3b, v109
	v_exp_f32_e32 v156, v156
	v_exp_f32_e32 v158, v157
	v_pk_mul_f32 v[98:99], v[98:99], v[188:189] op_sel_hi:[1,0]
	v_pk_mul_f32 v[100:101], v[100:101], v[188:189] op_sel_hi:[1,0]
	v_add_f32_e32 v156, 1.0, v156
	v_rcp_f32_e32 v157, v156
	v_add_f32_e32 v156, 1.0, v158
	v_rcp_f32_e32 v156, v156
	v_mov_b32_dpp v206, v98 row_shr:2 row_mask:0xf bank_mask:0xf
	v_mov_b32_dpp v207, v99 row_shr:2 row_mask:0xf bank_mask:0xf
	v_rcp_f32_e32 v154, v154
	v_mov_b32_dpp v112, v98 row_shr:1 row_mask:0xf bank_mask:0xf
	v_mov_b32_dpp v113, v99 row_shr:1 row_mask:0xf bank_mask:0xf
	v_mov_b32_dpp v106, v100 row_shr:2 row_mask:0xf bank_mask:0xf
	v_mov_b32_dpp v107, v101 row_shr:2 row_mask:0xf bank_mask:0xf
	v_pk_fma_f32 v[158:159], v[130:131], v[206:207], v[134:135]
	v_mov_b32_dpp v160, v100 row_shr:1 row_mask:0xf bank_mask:0xf
	v_mov_b32_dpp v161, v101 row_shr:1 row_mask:0xf bank_mask:0xf
	v_pk_fma_f32 v[106:107], v[132:133], v[106:107], v[136:137]
	v_pk_fma_f32 v[112:113], v[122:123], v[112:113], v[158:159]
	v_pk_fma_f32 v[106:107], v[124:125], v[160:161], v[106:107]
	v_pk_fma_f32 v[112:113], v[98:99], v[126:127], v[112:113]
	v_pk_mul_f32 v[108:109], v[108:109], v[156:157]
	v_pk_fma_f32 v[106:107], v[100:101], v[128:129], v[106:107]
	v_pk_mul_f32 v[108:109], v[108:109], v[112:113]
	v_pk_mul_f32 v[112:113], v[118:119], v[154:155]
	v_cvt_pk_bf16_f32 v108, v108, v109
	v_pk_mul_f32 v[106:107], v[112:113], v[106:107]
	v_or_b32_e32 v112, 48, v179
	v_mad_i64_i32 v[112:113], s[42:43], v112, s82, v[116:117]
	v_lshl_add_u64 v[112:113], v[112:113], 0, v[120:121]
	v_cvt_pk_bf16_f32 v109, v106, v107
	v_lshl_add_u64 v[106:107], s[20:21], 0, v[204:205]
	global_store_dwordx2 v[112:113], v[108:109], off
	v_lshl_add_u64 v[108:109], v[184:185], 2, v[106:107]
	s_and_saveexec_b64 s[62:63], s[10:11]
	s_cbranch_execz .LBB0_1427
	global_store_dwordx4 v[108:109], v[102:105], off
	s_nop 1
	v_add_co_u32_e32 v102, vcc, 0x2000, v108
	s_nop 1
	v_addc_co_u32_e32 v103, vcc, 0, v109, vcc
	global_store_dwordx4 v[102:103], v[98:101], off offset:3072
.LBB0_1427:
	s_or_b64 exec, exec, s[62:63]
	v_pk_mul_f32 v[96:97], v[96:97], v[186:187] op_sel_hi:[1,0]
	v_pk_mul_f32 v[94:95], v[94:95], v[186:187] op_sel_hi:[1,0]
	v_pk_mul_f32 v[92:93], v[92:93], v[186:187] op_sel_hi:[1,0]
	v_pk_mul_f32 v[90:91], v[90:91], v[186:187] op_sel_hi:[1,0]
	s_add_i32 s60, s60, 2
	v_mov_b32_dpp v102, v94 row_ror:1 row_mask:0xf bank_mask:0xf
	v_mov_b32_dpp v103, v95 row_ror:1 row_mask:0xf bank_mask:0xf
	v_mov_b32_dpp v116, v96 row_ror:1 row_mask:0xf bank_mask:0xf
	v_mov_b32_dpp v117, v97 row_ror:1 row_mask:0xf bank_mask:0xf
	v_mov_b32_dpp v154, v94 row_ror:2 row_mask:0xf bank_mask:0xf
	v_mov_b32_dpp v155, v95 row_ror:2 row_mask:0xf bank_mask:0xf
	v_mov_b32_dpp v156, v96 row_ror:2 row_mask:0xf bank_mask:0xf
	v_mov_b32_dpp v157, v97 row_ror:2 row_mask:0xf bank_mask:0xf
	v_mov_b32_dpp v98, v90 row_ror:1 row_mask:0xf bank_mask:0xf
	v_mov_b32_dpp v99, v91 row_ror:1 row_mask:0xf bank_mask:0xf
	v_mov_b32_dpp v100, v92 row_ror:1 row_mask:0xf bank_mask:0xf
	v_mov_b32_dpp v101, v93 row_ror:1 row_mask:0xf bank_mask:0xf
	v_mov_b32_dpp v104, v90 row_ror:2 row_mask:0xf bank_mask:0xf
	v_mov_b32_dpp v105, v91 row_ror:2 row_mask:0xf bank_mask:0xf
	v_mov_b32_dpp v118, v92 row_ror:2 row_mask:0xf bank_mask:0xf
	v_mov_b32_dpp v119, v93 row_ror:2 row_mask:0xf bank_mask:0xf
	v_lshl_or_b32 v158, s60, 6, v166
	v_mov_b32_dpp v102, v94 row_shr:1 row_mask:0xf bank_mask:0xf
	v_mov_b32_dpp v103, v95 row_shr:1 row_mask:0xf bank_mask:0xf
	v_mov_b32_dpp v116, v96 row_shr:1 row_mask:0xf bank_mask:0xf
	v_mov_b32_dpp v117, v97 row_shr:1 row_mask:0xf bank_mask:0xf
	v_mov_b32_dpp v154, v94 row_shr:2 row_mask:0xf bank_mask:0xf
	v_mov_b32_dpp v155, v95 row_shr:2 row_mask:0xf bank_mask:0xf
	v_mov_b32_dpp v156, v96 row_shr:2 row_mask:0xf bank_mask:0xf
	v_mov_b32_dpp v157, v97 row_shr:2 row_mask:0xf bank_mask:0xf
	v_mov_b32_dpp v98, v90 row_shr:1 row_mask:0xf bank_mask:0xf
	v_mov_b32_dpp v99, v91 row_shr:1 row_mask:0xf bank_mask:0xf
	v_mov_b32_dpp v100, v92 row_shr:1 row_mask:0xf bank_mask:0xf
	v_mov_b32_dpp v101, v93 row_shr:1 row_mask:0xf bank_mask:0xf
	v_mov_b32_dpp v104, v90 row_shr:2 row_mask:0xf bank_mask:0xf
	v_mov_b32_dpp v105, v91 row_shr:2 row_mask:0xf bank_mask:0xf
	v_mov_b32_dpp v118, v92 row_shr:2 row_mask:0xf bank_mask:0xf
	v_mov_b32_dpp v119, v93 row_shr:2 row_mask:0xf bank_mask:0xf
	s_and_saveexec_b64 s[62:63], s[6:7]
	s_cbranch_execz .LBB0_1429
	v_pk_fma_f32 v[156:157], v[148:149], v[156:157], v[152:153]
	v_pk_fma_f32 v[154:155], v[146:147], v[154:155], v[150:151]
	v_pk_fma_f32 v[116:117], v[144:145], v[116:117], v[156:157]
	v_pk_fma_f32 v[102:103], v[142:143], v[102:103], v[154:155]
	v_pk_fma_f32 v[116:117], v[96:97], v[140:141], v[116:117]
	v_pk_fma_f32 v[102:103], v[94:95], v[138:139], v[102:103]
	v_mul_f32_e32 v154, 0xbfb8aa3b, v117
	v_exp_f32_e32 v154, v154
	v_mul_f32_e32 v155, 0xbfb8aa3b, v116
	v_exp_f32_e32 v156, v155
	v_mul_f32_e32 v157, 0xbfb8aa3b, v102
	v_add_f32_e32 v154, 1.0, v154
	v_rcp_f32_e32 v155, v154
	v_add_f32_e32 v154, 1.0, v156
	v_mul_f32_e32 v156, 0xbfb8aa3b, v103
	v_exp_f32_e32 v156, v156
	v_exp_f32_e32 v159, v157
	v_rcp_f32_e32 v154, v154
	v_pk_fma_f32 v[104:105], v[130:131], v[104:105], v[134:135]
	v_add_f32_e32 v156, 1.0, v156
	v_rcp_f32_e32 v157, v156
	v_add_f32_e32 v156, 1.0, v159
	v_rcp_f32_e32 v156, v156
	v_pk_fma_f32 v[118:119], v[132:133], v[118:119], v[136:137]
	v_pk_fma_f32 v[98:99], v[122:123], v[98:99], v[104:105]
	v_pk_fma_f32 v[100:101], v[124:125], v[100:101], v[118:119]
	v_pk_fma_f32 v[98:99], v[90:91], v[126:127], v[98:99]
	v_pk_mul_f32 v[102:103], v[102:103], v[156:157]
	v_pk_fma_f32 v[100:101], v[92:93], v[128:129], v[100:101]
	v_pk_mul_f32 v[98:99], v[102:103], v[98:99]
	v_pk_mul_f32 v[102:103], v[116:117], v[154:155]
	v_cvt_pk_bf16_f32 v98, v98, v99
	v_pk_mul_f32 v[100:101], v[102:103], v[100:101]
	v_mov_b64_e32 v[102:103], s[18:19]
	v_mad_i64_i32 v[102:103], s[42:43], v158, s82, v[102:103]
	v_lshl_add_u64 v[102:103], v[184:185], 1, v[102:103]
	v_cvt_pk_bf16_f32 v99, v100, v101
	global_store_dwordx2 v[102:103], v[98:99], off

.LBB0_1431:
	s_or_b64 exec, exec, s[62:63]
	v_lshl_add_u64 v[104:105], s[60:61], 0, v[168:169]
	v_mad_u64_u32 v[102:103], s[42:43], v104, s83, 0
	v_mad_i32_i24 v103, v105, s83, v103
	v_pk_mul_f32 v[104:105], v[82:83], v[182:183] op_sel_hi:[1,0]
	v_mov_b32_dpp v82, v94 row_ror:1 row_mask:0xf bank_mask:0xf
	v_mov_b32_dpp v83, v95 row_ror:1 row_mask:0xf bank_mask:0xf
	v_mov_b32_dpp v118, v94 row_ror:2 row_mask:0xf bank_mask:0xf
	v_mov_b32_dpp v119, v95 row_ror:2 row_mask:0xf bank_mask:0xf
	v_pk_mul_f32 v[88:89], v[88:89], v[182:183] op_sel_hi:[1,0]
	v_mov_b32_dpp v94, v96 row_ror:2 row_mask:0xf bank_mask:0xf
	v_mov_b32_dpp v95, v97 row_ror:2 row_mask:0xf bank_mask:0xf
	v_pk_mul_f32 v[86:87], v[86:87], v[182:183] op_sel_hi:[1,0]
	v_mov_b32_dpp v116, v96 row_ror:1 row_mask:0xf bank_mask:0xf
	v_mov_b32_dpp v117, v97 row_ror:1 row_mask:0xf bank_mask:0xf
	v_mov_b32_dpp v94, v88 row_shr:2 row_mask:0xf bank_mask:0xf
	v_mov_b32_dpp v95, v89 row_shr:2 row_mask:0xf bank_mask:0xf
	v_mov_b32_dpp v116, v88 row_shr:1 row_mask:0xf bank_mask:0xf
	v_mov_b32_dpp v117, v89 row_shr:1 row_mask:0xf bank_mask:0xf
	v_mov_b32_dpp v118, v86 row_shr:2 row_mask:0xf bank_mask:0xf
	v_mov_b32_dpp v119, v87 row_shr:2 row_mask:0xf bank_mask:0xf
	v_mov_b32_dpp v96, v90 row_ror:1 row_mask:0xf bank_mask:0xf
	v_mov_b32_dpp v97, v91 row_ror:1 row_mask:0xf bank_mask:0xf
	v_mov_b32_dpp v156, v90 row_ror:2 row_mask:0xf bank_mask:0xf
	v_mov_b32_dpp v157, v91 row_ror:2 row_mask:0xf bank_mask:0xf
	v_pk_fma_f32 v[94:95], v[148:149], v[94:95], v[152:153]
	v_mov_b32_dpp v82, v86 row_shr:1 row_mask:0xf bank_mask:0xf
	v_mov_b32_dpp v83, v87 row_shr:1 row_mask:0xf bank_mask:0xf
	v_mov_b32_dpp v154, v92 row_ror:1 row_mask:0xf bank_mask:0xf
	v_mov_b32_dpp v155, v93 row_ror:1 row_mask:0xf bank_mask:0xf
	v_mov_b32_dpp v90, v92 row_ror:2 row_mask:0xf bank_mask:0xf
	v_mov_b32_dpp v91, v93 row_ror:2 row_mask:0xf bank_mask:0xf
	v_pk_fma_f32 v[92:93], v[146:147], v[118:119], v[150:151]
	v_pk_fma_f32 v[94:95], v[144:145], v[116:117], v[94:95]
	v_pk_fma_f32 v[82:83], v[142:143], v[82:83], v[92:93]
	v_pk_fma_f32 v[92:93], v[88:89], v[140:141], v[94:95]
	v_pk_fma_f32 v[82:83], v[86:87], v[138:139], v[82:83]
	v_mul_f32_e32 v94, 0xbfb8aa3b, v93
	v_exp_f32_e32 v94, v94
	v_mul_f32_e32 v95, 0xbfb8aa3b, v92
	v_exp_f32_e32 v116, v95
	v_mul_f32_e32 v117, 0xbfb8aa3b, v82
	v_add_f32_e32 v94, 1.0, v94
	v_rcp_f32_e32 v95, v94
	v_add_f32_e32 v94, 1.0, v116
	v_mul_f32_e32 v116, 0xbfb8aa3b, v83
	v_exp_f32_e32 v116, v116
	v_exp_f32_e32 v118, v117
	v_pk_mul_f32 v[84:85], v[84:85], v[182:183] op_sel_hi:[1,0]
	v_mov_b32_dpp v156, v104 row_shr:2 row_mask:0xf bank_mask:0xf
	v_add_f32_e32 v116, 1.0, v116
	v_rcp_f32_e32 v117, v116
	v_add_f32_e32 v116, 1.0, v118
	v_rcp_f32_e32 v116, v116
	v_mov_b32_dpp v157, v105 row_shr:2 row_mask:0xf bank_mask:0xf
	v_rcp_f32_e32 v94, v94
	v_mov_b32_dpp v96, v104 row_shr:1 row_mask:0xf bank_mask:0xf
	v_mov_b32_dpp v97, v105 row_shr:1 row_mask:0xf bank_mask:0xf
	v_mov_b32_dpp v90, v84 row_shr:2 row_mask:0xf bank_mask:0xf
	v_mov_b32_dpp v91, v85 row_shr:2 row_mask:0xf bank_mask:0xf
	v_pk_fma_f32 v[118:119], v[130:131], v[156:157], v[134:135]
	v_mov_b32_dpp v154, v84 row_shr:1 row_mask:0xf bank_mask:0xf
	v_mov_b32_dpp v155, v85 row_shr:1 row_mask:0xf bank_mask:0xf
	v_pk_fma_f32 v[90:91], v[132:133], v[90:91], v[136:137]
	v_pk_fma_f32 v[96:97], v[122:123], v[96:97], v[118:119]
	v_pk_fma_f32 v[90:91], v[124:125], v[154:155], v[90:91]
	v_pk_fma_f32 v[96:97], v[104:105], v[126:127], v[96:97]
	v_pk_mul_f32 v[82:83], v[82:83], v[116:117]
	v_pk_fma_f32 v[90:91], v[84:85], v[128:129], v[90:91]
	v_pk_mul_f32 v[96:97], v[82:83], v[96:97]
	v_pk_mul_f32 v[82:83], v[92:93], v[94:95]
	v_or_b32_e32 v92, 16, v158
	v_pk_mul_f32 v[90:91], v[82:83], v[90:91]
	v_mov_b64_e32 v[82:83], s[18:19]
	v_mad_i64_i32 v[92:93], s[42:43], v92, s82, v[82:83]
	v_lshl_add_u64 v[116:117], v[92:93], 0, v[120:121]
	v_cvt_pk_bf16_f32 v93, v90, v91
	v_cvt_pk_bf16_f32 v92, v96, v97
	v_mov_b32_dpp v90, v86 row_ror:1 row_mask:0xf bank_mask:0xf
	v_mov_b32_dpp v91, v87 row_ror:1 row_mask:0xf bank_mask:0xf
	v_mov_b32_dpp v94, v86 row_ror:2 row_mask:0xf bank_mask:0xf
	v_mov_b32_dpp v95, v87 row_ror:2 row_mask:0xf bank_mask:0xf
	global_store_dwordx2 v[116:117], v[92:93], off
	v_pk_mul_f32 v[80:81], v[80:81], v[180:181] op_sel_hi:[1,0]
	v_mov_b32_dpp v86, v88 row_ror:2 row_mask:0xf bank_mask:0xf
	v_mov_b32_dpp v87, v89 row_ror:2 row_mask:0xf bank_mask:0xf
	v_mov_b32_dpp v92, v88 row_ror:1 row_mask:0xf bank_mask:0xf
	v_mov_b32_dpp v93, v89 row_ror:1 row_mask:0xf bank_mask:0xf
	v_mov_b32_dpp v86, v80 row_shr:2 row_mask:0xf bank_mask:0xf
	v_mov_b32_dpp v87, v81 row_shr:2 row_mask:0xf bank_mask:0xf
	v_pk_mul_f32 v[78:79], v[78:79], v[180:181] op_sel_hi:[1,0]
	v_mov_b32_dpp v92, v80 row_shr:1 row_mask:0xf bank_mask:0xf
	v_mov_b32_dpp v93, v81 row_shr:1 row_mask:0xf bank_mask:0xf
	v_pk_fma_f32 v[86:87], v[148:149], v[86:87], v[152:153]
	v_mov_b32_dpp v94, v78 row_shr:2 row_mask:0xf bank_mask:0xf
	v_mov_b32_dpp v95, v79 row_shr:2 row_mask:0xf bank_mask:0xf
	v_mov_b32_dpp v88, v104 row_ror:1 row_mask:0xf bank_mask:0xf
	v_mov_b32_dpp v89, v105 row_ror:1 row_mask:0xf bank_mask:0xf
	v_mov_b32_dpp v118, v104 row_ror:2 row_mask:0xf bank_mask:0xf
	v_mov_b32_dpp v119, v105 row_ror:2 row_mask:0xf bank_mask:0xf
	v_pk_fma_f32 v[86:87], v[144:145], v[92:93], v[86:87]
	v_mov_b32_dpp v90, v78 row_shr:1 row_mask:0xf bank_mask:0xf
	v_mov_b32_dpp v91, v79 row_shr:1 row_mask:0xf bank_mask:0xf
	v_mov_b32_dpp v96, v84 row_ror:1 row_mask:0xf bank_mask:0xf
	v_mov_b32_dpp v97, v85 row_ror:1 row_mask:0xf bank_mask:0xf
	v_mov_b32_dpp v104, v84 row_ror:2 row_mask:0xf bank_mask:0xf
	v_mov_b32_dpp v105, v85 row_ror:2 row_mask:0xf bank_mask:0xf
	v_pk_fma_f32 v[84:85], v[146:147], v[94:95], v[150:151]
	v_pk_fma_f32 v[86:87], v[80:81], v[140:141], v[86:87]
	v_pk_fma_f32 v[84:85], v[142:143], v[90:91], v[84:85]
	v_mul_f32_e32 v90, 0xbfb8aa3b, v87
	v_exp_f32_e32 v90, v90
	v_mul_f32_e32 v91, 0xbfb8aa3b, v86
	v_exp_f32_e32 v92, v91
	v_pk_fma_f32 v[84:85], v[78:79], v[138:139], v[84:85]
	v_add_f32_e32 v90, 1.0, v90
	v_rcp_f32_e32 v91, v90
	v_add_f32_e32 v90, 1.0, v92
	v_mul_f32_e32 v92, 0xbfb8aa3b, v85
	v_exp_f32_e32 v92, v92
	v_mul_f32_e32 v93, 0xbfb8aa3b, v84
	v_exp_f32_e32 v94, v93
	v_pk_mul_f32 v[76:77], v[76:77], v[180:181] op_sel_hi:[1,0]
	v_add_f32_e32 v92, 1.0, v92
	v_rcp_f32_e32 v93, v92
	v_add_f32_e32 v92, 1.0, v94
	v_pk_mul_f32 v[74:75], v[74:75], v[180:181] op_sel_hi:[1,0]
	v_rcp_f32_e32 v92, v92
	v_mov_b32_dpp v104, v76 row_shr:2 row_mask:0xf bank_mask:0xf
	v_mov_b32_dpp v118, v74 row_shr:2 row_mask:0xf bank_mask:0xf
	v_mov_b32_dpp v119, v75 row_shr:2 row_mask:0xf bank_mask:0xf
	v_mov_b32_dpp v105, v77 row_shr:2 row_mask:0xf bank_mask:0xf
	v_rcp_f32_e32 v90, v90
	v_mov_b32_dpp v88, v74 row_shr:1 row_mask:0xf bank_mask:0xf
	v_mov_b32_dpp v89, v75 row_shr:1 row_mask:0xf bank_mask:0xf
	v_pk_fma_f32 v[94:95], v[132:133], v[104:105], v[136:137]
	v_pk_fma_f32 v[104:105], v[130:131], v[118:119], v[134:135]
	v_mov_b32_dpp v96, v76 row_shr:1 row_mask:0xf bank_mask:0xf
	v_mov_b32_dpp v97, v77 row_shr:1 row_mask:0xf bank_mask:0xf
	v_pk_fma_f32 v[88:89], v[122:123], v[88:89], v[104:105]
	v_pk_fma_f32 v[94:95], v[124:125], v[96:97], v[94:95]
	v_pk_fma_f32 v[88:89], v[74:75], v[126:127], v[88:89]
	v_pk_mul_f32 v[84:85], v[84:85], v[92:93]
	v_pk_fma_f32 v[94:95], v[76:77], v[128:129], v[94:95]
	v_pk_mul_f32 v[84:85], v[84:85], v[88:89]
	v_pk_mul_f32 v[86:87], v[86:87], v[90:91]
	v_or_b32_e32 v88, 32, v158
	v_pk_mul_f32 v[86:87], v[86:87], v[94:95]
	v_mad_i64_i32 v[88:89], s[42:43], v88, s82, v[82:83]
	v_lshl_add_u64 v[118:119], v[88:89], 0, v[120:121]
	v_cvt_pk_bf16_f32 v84, v84, v85
	v_cvt_pk_bf16_f32 v85, v86, v87
	global_store_dwordx2 v[118:119], v[84:85], off
	v_mov_b32_dpp v84, v78 row_ror:1 row_mask:0xf bank_mask:0xf
	v_mov_b32_dpp v85, v79 row_ror:1 row_mask:0xf bank_mask:0xf
	v_mov_b32_dpp v88, v78 row_ror:2 row_mask:0xf bank_mask:0xf
	v_mov_b32_dpp v89, v79 row_ror:2 row_mask:0xf bank_mask:0xf
	v_pk_mul_f32 v[72:73], v[72:73], v[178:179] op_sel_hi:[1,0]
	v_mov_b32_dpp v78, v80 row_ror:2 row_mask:0xf bank_mask:0xf
	v_mov_b32_dpp v79, v81 row_ror:2 row_mask:0xf bank_mask:0xf
	v_mov_b32_dpp v86, v80 row_ror:1 row_mask:0xf bank_mask:0xf
	v_mov_b32_dpp v87, v81 row_ror:1 row_mask:0xf bank_mask:0xf
	v_mov_b32_dpp v78, v72 row_shr:2 row_mask:0xf bank_mask:0xf
	v_mov_b32_dpp v79, v73 row_shr:2 row_mask:0xf bank_mask:0xf
	v_pk_mul_f32 v[70:71], v[70:71], v[178:179] op_sel_hi:[1,0]
	v_mov_b32_dpp v86, v72 row_shr:1 row_mask:0xf bank_mask:0xf
	v_mov_b32_dpp v87, v73 row_shr:1 row_mask:0xf bank_mask:0xf
	v_pk_fma_f32 v[78:79], v[148:149], v[78:79], v[152:153]
	v_mov_b32_dpp v88, v70 row_shr:2 row_mask:0xf bank_mask:0xf
	v_mov_b32_dpp v89, v71 row_shr:2 row_mask:0xf bank_mask:0xf
	v_mov_b32_dpp v80, v74 row_ror:1 row_mask:0xf bank_mask:0xf
	v_mov_b32_dpp v81, v75 row_ror:1 row_mask:0xf bank_mask:0xf
	v_mov_b32_dpp v92, v74 row_ror:2 row_mask:0xf bank_mask:0xf
	v_mov_b32_dpp v93, v75 row_ror:2 row_mask:0xf bank_mask:0xf
	v_pk_fma_f32 v[78:79], v[144:145], v[86:87], v[78:79]
	v_mov_b32_dpp v84, v70 row_shr:1 row_mask:0xf bank_mask:0xf
	v_mov_b32_dpp v85, v71 row_shr:1 row_mask:0xf bank_mask:0xf
	v_mov_b32_dpp v90, v76 row_ror:1 row_mask:0xf bank_mask:0xf
	v_mov_b32_dpp v91, v77 row_ror:1 row_mask:0xf bank_mask:0xf
	v_mov_b32_dpp v74, v76 row_ror:2 row_mask:0xf bank_mask:0xf
	v_mov_b32_dpp v75, v77 row_ror:2 row_mask:0xf bank_mask:0xf
	v_pk_fma_f32 v[76:77], v[146:147], v[88:89], v[150:151]
	v_pk_fma_f32 v[78:79], v[72:73], v[140:141], v[78:79]
	v_pk_fma_f32 v[76:77], v[142:143], v[84:85], v[76:77]
	v_mul_f32_e32 v84, 0xbfb8aa3b, v79
	v_exp_f32_e32 v84, v84
	v_mul_f32_e32 v85, 0xbfb8aa3b, v78
	v_exp_f32_e32 v86, v85
	v_pk_fma_f32 v[76:77], v[70:71], v[138:139], v[76:77]
	v_add_f32_e32 v84, 1.0, v84
	v_rcp_f32_e32 v85, v84
	v_add_f32_e32 v84, 1.0, v86
	v_mul_f32_e32 v86, 0xbfb8aa3b, v77
	v_exp_f32_e32 v86, v86
	v_mul_f32_e32 v87, 0xbfb8aa3b, v76
	v_exp_f32_e32 v88, v87
	v_pk_mul_f32 v[68:69], v[68:69], v[178:179] op_sel_hi:[1,0]
	v_add_f32_e32 v86, 1.0, v86
	v_rcp_f32_e32 v84, v84
	v_rcp_f32_e32 v87, v86
	v_add_f32_e32 v86, 1.0, v88
	v_pk_mul_f32 v[66:67], v[66:67], v[178:179] op_sel_hi:[1,0]
	v_mov_b32_dpp v74, v68 row_shr:2 row_mask:0xf bank_mask:0xf
	v_mov_b32_dpp v75, v69 row_shr:2 row_mask:0xf bank_mask:0xf
	v_rcp_f32_e32 v86, v86
	v_mov_b32_dpp v90, v68 row_shr:1 row_mask:0xf bank_mask:0xf
	v_mov_b32_dpp v91, v69 row_shr:1 row_mask:0xf bank_mask:0xf
	v_mov_b32_dpp v92, v66 row_shr:2 row_mask:0xf bank_mask:0xf
	v_mov_b32_dpp v93, v67 row_shr:2 row_mask:0xf bank_mask:0xf
	v_pk_fma_f32 v[74:75], v[132:133], v[74:75], v[136:137]
	v_mov_b32_dpp v80, v66 row_shr:1 row_mask:0xf bank_mask:0xf
	v_mov_b32_dpp v81, v67 row_shr:1 row_mask:0xf bank_mask:0xf
	v_pk_fma_f32 v[88:89], v[130:131], v[92:93], v[134:135]
	v_pk_fma_f32 v[74:75], v[124:125], v[90:91], v[74:75]
	v_pk_fma_f32 v[80:81], v[122:123], v[80:81], v[88:89]
	v_pk_fma_f32 v[74:75], v[68:69], v[128:129], v[74:75]
	v_pk_mul_f32 v[78:79], v[78:79], v[84:85]
	v_pk_fma_f32 v[80:81], v[66:67], v[126:127], v[80:81]
	v_pk_mul_f32 v[76:77], v[76:77], v[86:87]
	v_pk_mul_f32 v[74:75], v[78:79], v[74:75]
	v_or_b32_e32 v78, 48, v158
	v_pk_mul_f32 v[76:77], v[76:77], v[80:81]
	v_mad_i64_i32 v[78:79], s[42:43], v78, s82, v[82:83]
	v_lshl_add_u64 v[102:103], s[20:21], 0, v[102:103]
	v_lshl_add_u64 v[120:121], v[78:79], 0, v[120:121]
	v_cvt_pk_bf16_f32 v76, v76, v77
	v_cvt_pk_bf16_f32 v77, v74, v75
	v_lshl_add_u64 v[104:105], v[184:185], 2, v[102:103]
	global_store_dwordx2 v[120:121], v[76:77], off
	s_and_saveexec_b64 s[60:61], s[10:11]
	s_cbranch_execz .LBB0_1433
	global_store_dwordx4 v[104:105], v[70:73], off
	s_nop 1
	v_add_co_u32_e32 v70, vcc, 0x2000, v104
	s_nop 1
	v_addc_co_u32_e32 v71, vcc, 0, v105, vcc
	global_store_dwordx4 v[70:71], v[66:69], off offset:3072
.LBB0_1433:
	s_or_b64 exec, exec, s[60:61]
	v_or_b32_e32 v122, 64, v184
	v_ashrrev_i32_e32 v123, 31, v122
	v_lshlrev_b64 v[78:79], 2, v[122:123]
	v_lshl_add_u64 v[66:67], s[30:31], 0, v[78:79]
	v_lshl_add_u64 v[68:69], s[88:89], 0, v[78:79]
	global_load_dwordx4 v[90:93], v[196:197], off offset:256
	global_load_dwordx4 v[86:89], v[66:67], off
	global_load_dwordx4 v[82:85], v[68:69], off
	global_load_dwordx4 v[94:97], v[198:199], off offset:256
	v_lshl_add_u64 v[66:67], s[90:91], 0, v[78:79]
	v_lshl_add_u64 v[68:69], s[92:93], 0, v[78:79]
	v_lshl_add_u64 v[70:71], s[94:95], 0, v[78:79]
	v_lshl_add_u64 v[78:79], s[52:53], 0, v[78:79]
	global_load_dwordx4 v[74:77], v[66:67], off
	s_nop 0
	global_load_dwordx4 v[66:69], v[68:69], off
	v_mov_b32_e32 v195, v194
	global_load_dwordx4 v[70:73], v[70:71], off
	v_mov_b32_e32 v124, v194
	global_load_dwordx4 v[78:81], v[78:79], off
	v_mov_b32_e32 v125, v194
	v_pk_mul_f32 v[64:65], v[64:65], v[124:125]
	v_pk_mul_f32 v[62:63], v[62:63], v[194:195]
	v_pk_mul_f32 v[60:61], v[60:61], v[124:125]
	v_pk_mul_f32 v[58:59], v[58:59], v[194:195]
	v_mov_b32_dpp v128, v62 row_ror:1 row_mask:0xf bank_mask:0xf
	v_mov_b32_dpp v129, v63 row_ror:1 row_mask:0xf bank_mask:0xf
	v_mov_b32_dpp v132, v64 row_ror:1 row_mask:0xf bank_mask:0xf
	v_mov_b32_dpp v133, v65 row_ror:1 row_mask:0xf bank_mask:0xf
	v_mov_b32_dpp v136, v62 row_ror:2 row_mask:0xf bank_mask:0xf
	v_mov_b32_dpp v137, v63 row_ror:2 row_mask:0xf bank_mask:0xf
	v_mov_b32_dpp v138, v64 row_ror:2 row_mask:0xf bank_mask:0xf
	v_mov_b32_dpp v139, v65 row_ror:2 row_mask:0xf bank_mask:0xf
	v_mov_b32_dpp v124, v58 row_ror:1 row_mask:0xf bank_mask:0xf
	v_mov_b32_dpp v125, v59 row_ror:1 row_mask:0xf bank_mask:0xf
	v_mov_b32_dpp v126, v60 row_ror:1 row_mask:0xf bank_mask:0xf
	v_mov_b32_dpp v127, v61 row_ror:1 row_mask:0xf bank_mask:0xf
	v_mov_b32_dpp v130, v58 row_ror:2 row_mask:0xf bank_mask:0xf
	v_mov_b32_dpp v131, v59 row_ror:2 row_mask:0xf bank_mask:0xf
	v_mov_b32_dpp v134, v60 row_ror:2 row_mask:0xf bank_mask:0xf
	v_mov_b32_dpp v135, v61 row_ror:2 row_mask:0xf bank_mask:0xf
	v_mov_b32_dpp v128, v62 row_shr:1 row_mask:0xf bank_mask:0xf
	v_mov_b32_dpp v129, v63 row_shr:1 row_mask:0xf bank_mask:0xf
	v_mov_b32_dpp v132, v64 row_shr:1 row_mask:0xf bank_mask:0xf
	v_mov_b32_dpp v133, v65 row_shr:1 row_mask:0xf bank_mask:0xf
	v_mov_b32_dpp v136, v62 row_shr:2 row_mask:0xf bank_mask:0xf
	v_mov_b32_dpp v137, v63 row_shr:2 row_mask:0xf bank_mask:0xf
	v_mov_b32_dpp v138, v64 row_shr:2 row_mask:0xf bank_mask:0xf
	v_mov_b32_dpp v139, v65 row_shr:2 row_mask:0xf bank_mask:0xf
	v_mov_b32_dpp v124, v58 row_shr:1 row_mask:0xf bank_mask:0xf
	v_mov_b32_dpp v125, v59 row_shr:1 row_mask:0xf bank_mask:0xf
	v_mov_b32_dpp v126, v60 row_shr:1 row_mask:0xf bank_mask:0xf
	v_mov_b32_dpp v127, v61 row_shr:1 row_mask:0xf bank_mask:0xf
	v_mov_b32_dpp v130, v58 row_shr:2 row_mask:0xf bank_mask:0xf
	v_mov_b32_dpp v131, v59 row_shr:2 row_mask:0xf bank_mask:0xf
	v_mov_b32_dpp v134, v60 row_shr:2 row_mask:0xf bank_mask:0xf
	v_mov_b32_dpp v135, v61 row_shr:2 row_mask:0xf bank_mask:0xf
	s_and_saveexec_b64 s[60:61], s[6:7]
	s_cbranch_execz .LBB0_1435
	s_waitcnt vmcnt(0)
	v_pk_fma_f32 v[138:139], v[92:93], v[138:139], v[96:97]
	v_pk_fma_f32 v[136:137], v[90:91], v[136:137], v[94:95]
	v_pk_fma_f32 v[132:133], v[88:89], v[132:133], v[138:139]
	v_pk_fma_f32 v[128:129], v[86:87], v[128:129], v[136:137]
	v_pk_fma_f32 v[132:133], v[64:65], v[84:85], v[132:133]
	v_pk_fma_f32 v[128:129], v[62:63], v[82:83], v[128:129]
	v_mul_f32_e32 v136, 0xbfb8aa3b, v133
	v_exp_f32_e32 v136, v136
	v_mul_f32_e32 v137, 0xbfb8aa3b, v132
	v_exp_f32_e32 v138, v137
	v_mul_f32_e32 v139, 0xbfb8aa3b, v128
	v_add_f32_e32 v136, 1.0, v136
	v_rcp_f32_e32 v137, v136
	v_add_f32_e32 v136, 1.0, v138
	v_mul_f32_e32 v138, 0xbfb8aa3b, v129
	v_exp_f32_e32 v138, v138
	v_exp_f32_e32 v140, v139
	v_rcp_f32_e32 v136, v136
	v_pk_fma_f32 v[130:131], v[74:75], v[130:131], v[78:79]
	v_add_f32_e32 v138, 1.0, v138
	v_rcp_f32_e32 v139, v138
	v_add_f32_e32 v138, 1.0, v140
	v_rcp_f32_e32 v138, v138
	v_pk_fma_f32 v[134:135], v[76:77], v[134:135], v[80:81]
	v_pk_fma_f32 v[124:125], v[66:67], v[124:125], v[130:131]
	v_pk_fma_f32 v[126:127], v[68:69], v[126:127], v[134:135]
	v_pk_fma_f32 v[124:125], v[58:59], v[70:71], v[124:125]
	v_pk_mul_f32 v[128:129], v[128:129], v[138:139]
	v_pk_fma_f32 v[126:127], v[60:61], v[72:73], v[126:127]
	v_pk_mul_f32 v[124:125], v[128:129], v[124:125]
	v_pk_mul_f32 v[128:129], v[132:133], v[136:137]
	v_cvt_pk_bf16_f32 v124, v124, v125
	v_pk_mul_f32 v[126:127], v[128:129], v[126:127]
	v_mov_b64_e32 v[128:129], s[18:19]
	v_mad_i64_i32 v[128:129], s[42:43], v179, s82, v[128:129]
	v_lshl_add_u64 v[128:129], v[184:185], 1, v[128:129]
	v_cvt_pk_bf16_f32 v125, v126, v127
	global_store_dwordx2 v[128:129], v[124:125], off offset:128

.LBB0_1437:
	s_or_b64 exec, exec, s[60:61]
	v_mov_b32_e32 v124, v192
	v_mov_b32_e32 v125, v192
	v_pk_mul_f32 v[56:57], v[56:57], v[124:125]
	v_pk_mul_f32 v[52:53], v[52:53], v[124:125]
	v_mov_b32_dpp v124, v62 row_ror:1 row_mask:0xf bank_mask:0xf
	v_mov_b32_dpp v125, v63 row_ror:1 row_mask:0xf bank_mask:0xf
	v_mov_b32_dpp v128, v62 row_ror:2 row_mask:0xf bank_mask:0xf
	v_mov_b32_dpp v129, v63 row_ror:2 row_mask:0xf bank_mask:0xf
	v_mov_b32_dpp v62, v64 row_ror:2 row_mask:0xf bank_mask:0xf
	v_mov_b32_dpp v63, v65 row_ror:2 row_mask:0xf bank_mask:0xf
	v_mov_b32_e32 v193, v192
	v_mov_b32_dpp v126, v64 row_ror:1 row_mask:0xf bank_mask:0xf
	v_mov_b32_dpp v127, v65 row_ror:1 row_mask:0xf bank_mask:0xf
	v_mov_b32_dpp v62, v56 row_shr:2 row_mask:0xf bank_mask:0xf
	v_mov_b32_dpp v63, v57 row_shr:2 row_mask:0xf bank_mask:0xf
	v_pk_mul_f32 v[54:55], v[54:55], v[192:193]
	v_mov_b32_dpp v126, v56 row_shr:1 row_mask:0xf bank_mask:0xf
	v_mov_b32_dpp v127, v57 row_shr:1 row_mask:0xf bank_mask:0xf
	s_waitcnt vmcnt(0)
	v_pk_fma_f32 v[62:63], v[92:93], v[62:63], v[96:97]
	v_mov_b32_dpp v128, v54 row_shr:2 row_mask:0xf bank_mask:0xf
	v_mov_b32_dpp v129, v55 row_shr:2 row_mask:0xf bank_mask:0xf
	v_mov_b32_dpp v64, v58 row_ror:1 row_mask:0xf bank_mask:0xf
	v_mov_b32_dpp v65, v59 row_ror:1 row_mask:0xf bank_mask:0xf
	v_mov_b32_dpp v132, v58 row_ror:2 row_mask:0xf bank_mask:0xf
	v_mov_b32_dpp v133, v59 row_ror:2 row_mask:0xf bank_mask:0xf
	v_pk_fma_f32 v[62:63], v[88:89], v[126:127], v[62:63]
	v_mov_b32_dpp v124, v54 row_shr:1 row_mask:0xf bank_mask:0xf
	v_mov_b32_dpp v125, v55 row_shr:1 row_mask:0xf bank_mask:0xf
	v_mov_b32_dpp v130, v60 row_ror:1 row_mask:0xf bank_mask:0xf
	v_mov_b32_dpp v131, v61 row_ror:1 row_mask:0xf bank_mask:0xf
	v_mov_b32_dpp v58, v60 row_ror:2 row_mask:0xf bank_mask:0xf
	v_mov_b32_dpp v59, v61 row_ror:2 row_mask:0xf bank_mask:0xf
	v_pk_fma_f32 v[60:61], v[90:91], v[128:129], v[94:95]
	v_pk_fma_f32 v[62:63], v[56:57], v[84:85], v[62:63]
	v_pk_fma_f32 v[60:61], v[86:87], v[124:125], v[60:61]
	v_mul_f32_e32 v124, 0xbfb8aa3b, v63
	v_exp_f32_e32 v124, v124
	v_mul_f32_e32 v125, 0xbfb8aa3b, v62
	v_exp_f32_e32 v126, v125
	v_pk_fma_f32 v[60:61], v[54:55], v[82:83], v[60:61]
	v_add_f32_e32 v124, 1.0, v124
	v_rcp_f32_e32 v125, v124
	v_add_f32_e32 v124, 1.0, v126
	v_mul_f32_e32 v126, 0xbfb8aa3b, v61
	v_exp_f32_e32 v126, v126
	v_mul_f32_e32 v127, 0xbfb8aa3b, v60
	v_exp_f32_e32 v128, v127
	v_pk_mul_f32 v[50:51], v[50:51], v[192:193]
	v_add_f32_e32 v126, 1.0, v126
	v_rcp_f32_e32 v127, v126
	v_add_f32_e32 v126, 1.0, v128
	v_rcp_f32_e32 v124, v124
	v_rcp_f32_e32 v126, v126
	v_mov_b32_dpp v132, v50 row_shr:2 row_mask:0xf bank_mask:0xf
	v_mov_b32_dpp v133, v51 row_shr:2 row_mask:0xf bank_mask:0xf
	v_mov_b32_dpp v58, v52 row_shr:2 row_mask:0xf bank_mask:0xf
	v_mov_b32_dpp v59, v53 row_shr:2 row_mask:0xf bank_mask:0xf
	v_mov_b32_dpp v64, v50 row_shr:1 row_mask:0xf bank_mask:0xf
	v_mov_b32_dpp v65, v51 row_shr:1 row_mask:0xf bank_mask:0xf
	v_mov_b32_dpp v130, v52 row_shr:1 row_mask:0xf bank_mask:0xf
	v_mov_b32_dpp v131, v53 row_shr:1 row_mask:0xf bank_mask:0xf
	v_pk_fma_f32 v[58:59], v[76:77], v[58:59], v[80:81]
	v_pk_fma_f32 v[128:129], v[74:75], v[132:133], v[78:79]
	v_pk_fma_f32 v[58:59], v[68:69], v[130:131], v[58:59]
	v_pk_fma_f32 v[64:65], v[66:67], v[64:65], v[128:129]
	v_pk_fma_f32 v[58:59], v[52:53], v[72:73], v[58:59]
	v_pk_fma_f32 v[64:65], v[50:51], v[70:71], v[64:65]
	v_pk_mul_f32 v[60:61], v[60:61], v[126:127]
	v_pk_mul_f32 v[62:63], v[62:63], v[124:125]
	v_pk_mul_f32 v[60:61], v[60:61], v[64:65]
	v_pk_mul_f32 v[58:59], v[62:63], v[58:59]
	v_cvt_pk_bf16_f32 v60, v60, v61
	v_cvt_pk_bf16_f32 v61, v58, v59
	v_mov_b32_e32 v58, v190
	v_mov_b32_e32 v59, v190
	v_pk_mul_f32 v[48:49], v[48:49], v[58:59]
	v_pk_mul_f32 v[44:45], v[44:45], v[58:59]
	global_store_dwordx2 v[114:115], v[60:61], off offset:128
	v_mov_b32_dpp v58, v54 row_ror:1 row_mask:0xf bank_mask:0xf
	v_mov_b32_dpp v59, v55 row_ror:1 row_mask:0xf bank_mask:0xf
	v_mov_b32_dpp v62, v54 row_ror:2 row_mask:0xf bank_mask:0xf
	v_mov_b32_dpp v63, v55 row_ror:2 row_mask:0xf bank_mask:0xf
	v_mov_b32_dpp v60, v56 row_ror:1 row_mask:0xf bank_mask:0xf
	v_mov_b32_dpp v61, v57 row_ror:1 row_mask:0xf bank_mask:0xf
	v_mov_b32_dpp v54, v56 row_ror:2 row_mask:0xf bank_mask:0xf
	v_mov_b32_dpp v55, v57 row_ror:2 row_mask:0xf bank_mask:0xf
	v_mov_b32_e32 v191, v190
	v_mov_b32_dpp v54, v48 row_shr:2 row_mask:0xf bank_mask:0xf
	v_mov_b32_dpp v55, v49 row_shr:2 row_mask:0xf bank_mask:0xf
	v_mov_b32_dpp v56, v50 row_ror:1 row_mask:0xf bank_mask:0xf
	v_mov_b32_dpp v57, v51 row_ror:1 row_mask:0xf bank_mask:0xf
	v_mov_b32_dpp v114, v50 row_ror:2 row_mask:0xf bank_mask:0xf
	v_mov_b32_dpp v115, v51 row_ror:2 row_mask:0xf bank_mask:0xf
	v_pk_mul_f32 v[46:47], v[46:47], v[190:191]
	v_mov_b32_dpp v60, v48 row_shr:1 row_mask:0xf bank_mask:0xf
	v_mov_b32_dpp v61, v49 row_shr:1 row_mask:0xf bank_mask:0xf
	v_mov_b32_dpp v64, v52 row_ror:1 row_mask:0xf bank_mask:0xf
	v_mov_b32_dpp v65, v53 row_ror:1 row_mask:0xf bank_mask:0xf
	v_mov_b32_dpp v50, v52 row_ror:2 row_mask:0xf bank_mask:0xf
	v_mov_b32_dpp v51, v53 row_ror:2 row_mask:0xf bank_mask:0xf
	v_pk_fma_f32 v[52:53], v[92:93], v[54:55], v[96:97]
	v_mov_b32_dpp v62, v46 row_shr:2 row_mask:0xf bank_mask:0xf
	v_mov_b32_dpp v63, v47 row_shr:2 row_mask:0xf bank_mask:0xf
	v_pk_fma_f32 v[52:53], v[88:89], v[60:61], v[52:53]
	v_mov_b32_dpp v58, v46 row_shr:1 row_mask:0xf bank_mask:0xf
	v_mov_b32_dpp v59, v47 row_shr:1 row_mask:0xf bank_mask:0xf
	v_pk_fma_f32 v[54:55], v[90:91], v[62:63], v[94:95]
	v_pk_fma_f32 v[52:53], v[48:49], v[84:85], v[52:53]
	v_pk_fma_f32 v[54:55], v[86:87], v[58:59], v[54:55]
	v_mul_f32_e32 v58, 0xbfb8aa3b, v53
	v_exp_f32_e32 v58, v58
	v_mul_f32_e32 v59, 0xbfb8aa3b, v52
	v_exp_f32_e32 v60, v59
	v_pk_fma_f32 v[54:55], v[46:47], v[82:83], v[54:55]
	v_add_f32_e32 v58, 1.0, v58
	v_rcp_f32_e32 v59, v58
	v_add_f32_e32 v58, 1.0, v60
	v_mul_f32_e32 v60, 0xbfb8aa3b, v55
	v_exp_f32_e32 v60, v60
	v_mul_f32_e32 v61, 0xbfb8aa3b, v54
	v_exp_f32_e32 v62, v61
	v_rcp_f32_e32 v58, v58
	v_add_f32_e32 v60, 1.0, v60
	v_rcp_f32_e32 v61, v60
	v_add_f32_e32 v60, 1.0, v62
	v_pk_mul_f32 v[42:43], v[42:43], v[190:191]
	v_mov_b32_dpp v50, v44 row_shr:2 row_mask:0xf bank_mask:0xf
	v_mov_b32_dpp v51, v45 row_shr:2 row_mask:0xf bank_mask:0xf
	v_rcp_f32_e32 v60, v60
	v_mov_b32_dpp v64, v44 row_shr:1 row_mask:0xf bank_mask:0xf
	v_mov_b32_dpp v65, v45 row_shr:1 row_mask:0xf bank_mask:0xf
	v_mov_b32_dpp v114, v42 row_shr:2 row_mask:0xf bank_mask:0xf
	v_mov_b32_dpp v115, v43 row_shr:2 row_mask:0xf bank_mask:0xf
	v_pk_fma_f32 v[50:51], v[76:77], v[50:51], v[80:81]
	v_mov_b32_dpp v56, v42 row_shr:1 row_mask:0xf bank_mask:0xf
	v_mov_b32_dpp v57, v43 row_shr:1 row_mask:0xf bank_mask:0xf
	v_pk_fma_f32 v[62:63], v[74:75], v[114:115], v[78:79]
	v_pk_fma_f32 v[50:51], v[68:69], v[64:65], v[50:51]
	v_pk_fma_f32 v[56:57], v[66:67], v[56:57], v[62:63]
	v_pk_fma_f32 v[50:51], v[44:45], v[72:73], v[50:51]
	v_pk_mul_f32 v[52:53], v[52:53], v[58:59]
	v_pk_fma_f32 v[56:57], v[42:43], v[70:71], v[56:57]
	v_pk_mul_f32 v[54:55], v[54:55], v[60:61]
	v_pk_mul_f32 v[50:51], v[52:53], v[50:51]
	v_pk_mul_f32 v[54:55], v[54:55], v[56:57]
	v_cvt_pk_bf16_f32 v53, v50, v51
	v_mov_b32_e32 v50, v188
	v_mov_b32_e32 v51, v188
	v_cvt_pk_bf16_f32 v52, v54, v55
	v_pk_mul_f32 v[40:41], v[40:41], v[50:51]
	v_pk_mul_f32 v[36:37], v[36:37], v[50:51]
	global_store_dwordx2 v[110:111], v[52:53], off offset:128
	v_mov_b32_dpp v50, v46 row_ror:1 row_mask:0xf bank_mask:0xf
	v_mov_b32_dpp v51, v47 row_ror:1 row_mask:0xf bank_mask:0xf
	v_mov_b32_dpp v54, v46 row_ror:2 row_mask:0xf bank_mask:0xf
	v_mov_b32_dpp v55, v47 row_ror:2 row_mask:0xf bank_mask:0xf
	v_mov_b32_dpp v52, v48 row_ror:1 row_mask:0xf bank_mask:0xf
	v_mov_b32_dpp v53, v49 row_ror:1 row_mask:0xf bank_mask:0xf
	v_mov_b32_dpp v46, v48 row_ror:2 row_mask:0xf bank_mask:0xf
	v_mov_b32_dpp v47, v49 row_ror:2 row_mask:0xf bank_mask:0xf
	v_mov_b32_e32 v189, v188
	v_mov_b32_dpp v46, v40 row_shr:2 row_mask:0xf bank_mask:0xf
	v_mov_b32_dpp v47, v41 row_shr:2 row_mask:0xf bank_mask:0xf
	v_mov_b32_dpp v48, v42 row_ror:1 row_mask:0xf bank_mask:0xf
	v_mov_b32_dpp v49, v43 row_ror:1 row_mask:0xf bank_mask:0xf
	v_mov_b32_dpp v58, v42 row_ror:2 row_mask:0xf bank_mask:0xf
	v_mov_b32_dpp v59, v43 row_ror:2 row_mask:0xf bank_mask:0xf
	v_pk_mul_f32 v[38:39], v[38:39], v[188:189]
	v_mov_b32_dpp v52, v40 row_shr:1 row_mask:0xf bank_mask:0xf
	v_mov_b32_dpp v53, v41 row_shr:1 row_mask:0xf bank_mask:0xf
	v_mov_b32_dpp v56, v44 row_ror:1 row_mask:0xf bank_mask:0xf
	v_mov_b32_dpp v57, v45 row_ror:1 row_mask:0xf bank_mask:0xf
	v_mov_b32_dpp v42, v44 row_ror:2 row_mask:0xf bank_mask:0xf
	v_mov_b32_dpp v43, v45 row_ror:2 row_mask:0xf bank_mask:0xf
	v_pk_fma_f32 v[44:45], v[92:93], v[46:47], v[96:97]
	v_mov_b32_dpp v54, v38 row_shr:2 row_mask:0xf bank_mask:0xf
	v_mov_b32_dpp v55, v39 row_shr:2 row_mask:0xf bank_mask:0xf
	v_pk_fma_f32 v[44:45], v[88:89], v[52:53], v[44:45]
	v_mov_b32_dpp v50, v38 row_shr:1 row_mask:0xf bank_mask:0xf
	v_mov_b32_dpp v51, v39 row_shr:1 row_mask:0xf bank_mask:0xf
	v_pk_fma_f32 v[46:47], v[90:91], v[54:55], v[94:95]
	v_pk_fma_f32 v[44:45], v[40:41], v[84:85], v[44:45]
	v_pk_fma_f32 v[46:47], v[86:87], v[50:51], v[46:47]
	v_mul_f32_e32 v50, 0xbfb8aa3b, v45
	v_exp_f32_e32 v50, v50
	v_mul_f32_e32 v51, 0xbfb8aa3b, v44
	v_exp_f32_e32 v52, v51
	v_pk_fma_f32 v[46:47], v[38:39], v[82:83], v[46:47]
	v_add_f32_e32 v50, 1.0, v50
	v_rcp_f32_e32 v51, v50
	v_add_f32_e32 v50, 1.0, v52
	v_mul_f32_e32 v52, 0xbfb8aa3b, v47
	v_exp_f32_e32 v52, v52
	v_mul_f32_e32 v53, 0xbfb8aa3b, v46
	v_exp_f32_e32 v54, v53
	v_pk_mul_f32 v[34:35], v[34:35], v[188:189]
	v_add_f32_e32 v52, 1.0, v52
	v_rcp_f32_e32 v53, v52
	v_add_f32_e32 v52, 1.0, v54
	v_rcp_f32_e32 v50, v50
	v_rcp_f32_e32 v52, v52
	v_mov_b32_dpp v58, v34 row_shr:2 row_mask:0xf bank_mask:0xf
	v_mov_b32_dpp v59, v35 row_shr:2 row_mask:0xf bank_mask:0xf
	v_mov_b32_dpp v42, v36 row_shr:2 row_mask:0xf bank_mask:0xf
	v_mov_b32_dpp v43, v37 row_shr:2 row_mask:0xf bank_mask:0xf
	v_mov_b32_dpp v48, v34 row_shr:1 row_mask:0xf bank_mask:0xf
	v_mov_b32_dpp v49, v35 row_shr:1 row_mask:0xf bank_mask:0xf
	v_mov_b32_dpp v56, v36 row_shr:1 row_mask:0xf bank_mask:0xf
	v_mov_b32_dpp v57, v37 row_shr:1 row_mask:0xf bank_mask:0xf
	v_pk_fma_f32 v[42:43], v[76:77], v[42:43], v[80:81]
	v_pk_fma_f32 v[54:55], v[74:75], v[58:59], v[78:79]
	v_pk_fma_f32 v[42:43], v[68:69], v[56:57], v[42:43]
	v_pk_fma_f32 v[48:49], v[66:67], v[48:49], v[54:55]
	v_pk_fma_f32 v[42:43], v[36:37], v[72:73], v[42:43]
	v_pk_fma_f32 v[48:49], v[34:35], v[70:71], v[48:49]
	v_pk_mul_f32 v[46:47], v[46:47], v[52:53]
	v_pk_mul_f32 v[44:45], v[44:45], v[50:51]
	v_pk_mul_f32 v[46:47], v[46:47], v[48:49]
	v_pk_mul_f32 v[42:43], v[44:45], v[42:43]
	v_cvt_pk_bf16_f32 v44, v46, v47
	v_cvt_pk_bf16_f32 v45, v42, v43
	global_store_dwordx2 v[112:113], v[44:45], off offset:128
	s_and_saveexec_b64 s[60:61], s[10:11]
	s_cbranch_execz .LBB0_1439
	v_lshl_add_u64 v[42:43], v[122:123], 2, v[106:107]
	global_store_dwordx4 v[108:109], v[38:41], off offset:256
	s_nop 1
	v_add_co_u32_e32 v38, vcc, 0x2000, v42
	s_nop 1
	v_addc_co_u32_e32 v39, vcc, 0, v43, vcc
	global_store_dwordx4 v[38:39], v[34:37], off offset:3072
.LBB0_1439:
	s_or_b64 exec, exec, s[60:61]
	v_mov_b32_e32 v187, v186
	v_mov_b32_e32 v34, v186
	v_mov_b32_e32 v35, v186
	v_pk_mul_f32 v[32:33], v[32:33], v[34:35]
	v_pk_mul_f32 v[30:31], v[30:31], v[186:187]
	v_pk_mul_f32 v[28:29], v[28:29], v[34:35]
	v_pk_mul_f32 v[26:27], v[26:27], v[186:187]
	v_mov_b32_dpp v38, v30 row_ror:1 row_mask:0xf bank_mask:0xf
	v_mov_b32_dpp v39, v31 row_ror:1 row_mask:0xf bank_mask:0xf
	v_mov_b32_dpp v42, v32 row_ror:1 row_mask:0xf bank_mask:0xf
	v_mov_b32_dpp v43, v33 row_ror:1 row_mask:0xf bank_mask:0xf
	v_mov_b32_dpp v46, v30 row_ror:2 row_mask:0xf bank_mask:0xf
	v_mov_b32_dpp v47, v31 row_ror:2 row_mask:0xf bank_mask:0xf
	v_mov_b32_dpp v48, v32 row_ror:2 row_mask:0xf bank_mask:0xf
	v_mov_b32_dpp v49, v33 row_ror:2 row_mask:0xf bank_mask:0xf
	v_mov_b32_dpp v34, v26 row_ror:1 row_mask:0xf bank_mask:0xf
	v_mov_b32_dpp v35, v27 row_ror:1 row_mask:0xf bank_mask:0xf
	v_mov_b32_dpp v36, v28 row_ror:1 row_mask:0xf bank_mask:0xf
	v_mov_b32_dpp v37, v29 row_ror:1 row_mask:0xf bank_mask:0xf
	v_mov_b32_dpp v40, v26 row_ror:2 row_mask:0xf bank_mask:0xf
	v_mov_b32_dpp v41, v27 row_ror:2 row_mask:0xf bank_mask:0xf
	v_mov_b32_dpp v44, v28 row_ror:2 row_mask:0xf bank_mask:0xf
	v_mov_b32_dpp v45, v29 row_ror:2 row_mask:0xf bank_mask:0xf
	v_mov_b32_dpp v38, v30 row_shr:1 row_mask:0xf bank_mask:0xf
	v_mov_b32_dpp v39, v31 row_shr:1 row_mask:0xf bank_mask:0xf
	v_mov_b32_dpp v42, v32 row_shr:1 row_mask:0xf bank_mask:0xf
	v_mov_b32_dpp v43, v33 row_shr:1 row_mask:0xf bank_mask:0xf
	v_mov_b32_dpp v46, v30 row_shr:2 row_mask:0xf bank_mask:0xf
	v_mov_b32_dpp v47, v31 row_shr:2 row_mask:0xf bank_mask:0xf
	v_mov_b32_dpp v48, v32 row_shr:2 row_mask:0xf bank_mask:0xf
	v_mov_b32_dpp v49, v33 row_shr:2 row_mask:0xf bank_mask:0xf
	v_mov_b32_dpp v34, v26 row_shr:1 row_mask:0xf bank_mask:0xf
	v_mov_b32_dpp v35, v27 row_shr:1 row_mask:0xf bank_mask:0xf
	v_mov_b32_dpp v36, v28 row_shr:1 row_mask:0xf bank_mask:0xf
	v_mov_b32_dpp v37, v29 row_shr:1 row_mask:0xf bank_mask:0xf
	v_mov_b32_dpp v40, v26 row_shr:2 row_mask:0xf bank_mask:0xf
	v_mov_b32_dpp v41, v27 row_shr:2 row_mask:0xf bank_mask:0xf
	v_mov_b32_dpp v44, v28 row_shr:2 row_mask:0xf bank_mask:0xf
	v_mov_b32_dpp v45, v29 row_shr:2 row_mask:0xf bank_mask:0xf
	s_and_saveexec_b64 s[60:61], s[6:7]
	s_cbranch_execz .LBB0_1441
	v_pk_fma_f32 v[48:49], v[92:93], v[48:49], v[96:97]
	v_pk_fma_f32 v[46:47], v[90:91], v[46:47], v[94:95]
	v_pk_fma_f32 v[42:43], v[88:89], v[42:43], v[48:49]
	v_pk_fma_f32 v[38:39], v[86:87], v[38:39], v[46:47]
	v_pk_fma_f32 v[42:43], v[32:33], v[84:85], v[42:43]
	v_pk_fma_f32 v[38:39], v[30:31], v[82:83], v[38:39]
	v_mul_f32_e32 v46, 0xbfb8aa3b, v43
	v_exp_f32_e32 v46, v46
	v_mul_f32_e32 v47, 0xbfb8aa3b, v42
	v_exp_f32_e32 v48, v47
	v_mul_f32_e32 v49, 0xbfb8aa3b, v38
	v_add_f32_e32 v46, 1.0, v46
	v_rcp_f32_e32 v47, v46
	v_add_f32_e32 v46, 1.0, v48
	v_mul_f32_e32 v48, 0xbfb8aa3b, v39
	v_exp_f32_e32 v48, v48
	v_exp_f32_e32 v50, v49
	v_rcp_f32_e32 v46, v46
	v_pk_fma_f32 v[40:41], v[74:75], v[40:41], v[78:79]
	v_add_f32_e32 v48, 1.0, v48
	v_rcp_f32_e32 v49, v48
	v_add_f32_e32 v48, 1.0, v50
	v_rcp_f32_e32 v48, v48
	v_pk_fma_f32 v[44:45], v[76:77], v[44:45], v[80:81]
	v_pk_fma_f32 v[34:35], v[66:67], v[34:35], v[40:41]
	v_pk_fma_f32 v[36:37], v[68:69], v[36:37], v[44:45]
	v_pk_fma_f32 v[34:35], v[26:27], v[70:71], v[34:35]
	v_pk_mul_f32 v[38:39], v[38:39], v[48:49]
	v_pk_fma_f32 v[36:37], v[28:29], v[72:73], v[36:37]
	v_pk_mul_f32 v[34:35], v[38:39], v[34:35]
	v_pk_mul_f32 v[38:39], v[42:43], v[46:47]
	v_cvt_pk_bf16_f32 v34, v34, v35
	v_pk_mul_f32 v[36:37], v[38:39], v[36:37]
	v_mov_b64_e32 v[38:39], s[18:19]
	v_mad_i64_i32 v[38:39], s[42:43], v158, s82, v[38:39]
	v_lshl_add_u64 v[38:39], v[184:185], 1, v[38:39]
	v_cvt_pk_bf16_f32 v35, v36, v37
	global_store_dwordx2 v[38:39], v[34:35], off offset:128

.LBB0_1443:
	s_or_b64 exec, exec, s[60:61]
	v_mov_b32_e32 v34, v182
	v_mov_b32_e32 v35, v182
	v_pk_mul_f32 v[24:25], v[24:25], v[34:35]
	v_pk_mul_f32 v[20:21], v[20:21], v[34:35]
	v_mov_b32_dpp v34, v30 row_ror:1 row_mask:0xf bank_mask:0xf
	v_mov_b32_dpp v35, v31 row_ror:1 row_mask:0xf bank_mask:0xf
	v_mov_b32_dpp v38, v30 row_ror:2 row_mask:0xf bank_mask:0xf
	v_mov_b32_dpp v39, v31 row_ror:2 row_mask:0xf bank_mask:0xf
	v_mov_b32_dpp v30, v32 row_ror:2 row_mask:0xf bank_mask:0xf
	v_mov_b32_dpp v31, v33 row_ror:2 row_mask:0xf bank_mask:0xf
	v_mov_b32_e32 v183, v182
	v_mov_b32_dpp v36, v32 row_ror:1 row_mask:0xf bank_mask:0xf
	v_mov_b32_dpp v37, v33 row_ror:1 row_mask:0xf bank_mask:0xf
	v_mov_b32_dpp v30, v24 row_shr:2 row_mask:0xf bank_mask:0xf
	v_mov_b32_dpp v31, v25 row_shr:2 row_mask:0xf bank_mask:0xf
	v_pk_mul_f32 v[22:23], v[22:23], v[182:183]
	v_mov_b32_dpp v36, v24 row_shr:1 row_mask:0xf bank_mask:0xf
	v_mov_b32_dpp v37, v25 row_shr:1 row_mask:0xf bank_mask:0xf
	v_pk_fma_f32 v[30:31], v[92:93], v[30:31], v[96:97]
	v_mov_b32_dpp v38, v22 row_shr:2 row_mask:0xf bank_mask:0xf
	v_mov_b32_dpp v39, v23 row_shr:2 row_mask:0xf bank_mask:0xf
	v_mov_b32_dpp v32, v26 row_ror:1 row_mask:0xf bank_mask:0xf
	v_mov_b32_dpp v33, v27 row_ror:1 row_mask:0xf bank_mask:0xf
	v_mov_b32_dpp v42, v26 row_ror:2 row_mask:0xf bank_mask:0xf
	v_mov_b32_dpp v43, v27 row_ror:2 row_mask:0xf bank_mask:0xf
	v_pk_fma_f32 v[30:31], v[88:89], v[36:37], v[30:31]
	v_mov_b32_dpp v34, v22 row_shr:1 row_mask:0xf bank_mask:0xf
	v_mov_b32_dpp v35, v23 row_shr:1 row_mask:0xf bank_mask:0xf
	v_mov_b32_dpp v40, v28 row_ror:1 row_mask:0xf bank_mask:0xf
	v_mov_b32_dpp v41, v29 row_ror:1 row_mask:0xf bank_mask:0xf
	v_mov_b32_dpp v26, v28 row_ror:2 row_mask:0xf bank_mask:0xf
	v_mov_b32_dpp v27, v29 row_ror:2 row_mask:0xf bank_mask:0xf
	v_pk_fma_f32 v[28:29], v[90:91], v[38:39], v[94:95]
	v_pk_fma_f32 v[30:31], v[24:25], v[84:85], v[30:31]
	v_pk_fma_f32 v[28:29], v[86:87], v[34:35], v[28:29]
	v_mul_f32_e32 v34, 0xbfb8aa3b, v31
	v_exp_f32_e32 v34, v34
	v_mul_f32_e32 v35, 0xbfb8aa3b, v30
	v_exp_f32_e32 v36, v35
	v_pk_fma_f32 v[28:29], v[22:23], v[82:83], v[28:29]
	v_add_f32_e32 v34, 1.0, v34
	v_rcp_f32_e32 v35, v34
	v_add_f32_e32 v34, 1.0, v36
	v_mul_f32_e32 v36, 0xbfb8aa3b, v29
	v_exp_f32_e32 v36, v36
	v_mul_f32_e32 v37, 0xbfb8aa3b, v28
	v_exp_f32_e32 v38, v37
	v_pk_mul_f32 v[18:19], v[18:19], v[182:183]
	v_add_f32_e32 v36, 1.0, v36
	v_rcp_f32_e32 v37, v36
	v_add_f32_e32 v36, 1.0, v38
	v_rcp_f32_e32 v34, v34
	v_rcp_f32_e32 v36, v36
	v_mov_b32_dpp v42, v18 row_shr:2 row_mask:0xf bank_mask:0xf
	v_mov_b32_dpp v43, v19 row_shr:2 row_mask:0xf bank_mask:0xf
	v_mov_b32_dpp v26, v20 row_shr:2 row_mask:0xf bank_mask:0xf
	v_mov_b32_dpp v27, v21 row_shr:2 row_mask:0xf bank_mask:0xf
	v_mov_b32_dpp v32, v18 row_shr:1 row_mask:0xf bank_mask:0xf
	v_mov_b32_dpp v33, v19 row_shr:1 row_mask:0xf bank_mask:0xf
	v_mov_b32_dpp v40, v20 row_shr:1 row_mask:0xf bank_mask:0xf
	v_mov_b32_dpp v41, v21 row_shr:1 row_mask:0xf bank_mask:0xf
	v_pk_fma_f32 v[26:27], v[76:77], v[26:27], v[80:81]
	v_pk_fma_f32 v[38:39], v[74:75], v[42:43], v[78:79]
	v_pk_fma_f32 v[26:27], v[68:69], v[40:41], v[26:27]
	v_pk_fma_f32 v[32:33], v[66:67], v[32:33], v[38:39]
	v_pk_fma_f32 v[26:27], v[20:21], v[72:73], v[26:27]
	v_pk_fma_f32 v[32:33], v[18:19], v[70:71], v[32:33]
	v_pk_mul_f32 v[28:29], v[28:29], v[36:37]
	v_pk_mul_f32 v[30:31], v[30:31], v[34:35]
	v_pk_mul_f32 v[28:29], v[28:29], v[32:33]
	v_pk_mul_f32 v[26:27], v[30:31], v[26:27]
	v_cvt_pk_bf16_f32 v28, v28, v29
	v_cvt_pk_bf16_f32 v29, v26, v27
	v_mov_b32_e32 v26, v180
	v_mov_b32_e32 v27, v180
	v_pk_mul_f32 v[16:17], v[16:17], v[26:27]
	v_pk_mul_f32 v[12:13], v[12:13], v[26:27]
	global_store_dwordx2 v[116:117], v[28:29], off offset:128
	v_mov_b32_dpp v26, v22 row_ror:1 row_mask:0xf bank_mask:0xf
	v_mov_b32_dpp v27, v23 row_ror:1 row_mask:0xf bank_mask:0xf
	v_mov_b32_dpp v30, v22 row_ror:2 row_mask:0xf bank_mask:0xf
	v_mov_b32_dpp v31, v23 row_ror:2 row_mask:0xf bank_mask:0xf
	v_mov_b32_dpp v28, v24 row_ror:1 row_mask:0xf bank_mask:0xf
	v_mov_b32_dpp v29, v25 row_ror:1 row_mask:0xf bank_mask:0xf
	v_mov_b32_dpp v22, v24 row_ror:2 row_mask:0xf bank_mask:0xf
	v_mov_b32_dpp v23, v25 row_ror:2 row_mask:0xf bank_mask:0xf
	v_mov_b32_e32 v181, v180
	v_mov_b32_dpp v22, v16 row_shr:2 row_mask:0xf bank_mask:0xf
	v_mov_b32_dpp v23, v17 row_shr:2 row_mask:0xf bank_mask:0xf
	v_mov_b32_dpp v24, v18 row_ror:1 row_mask:0xf bank_mask:0xf
	v_mov_b32_dpp v25, v19 row_ror:1 row_mask:0xf bank_mask:0xf
	v_mov_b32_dpp v34, v18 row_ror:2 row_mask:0xf bank_mask:0xf
	v_mov_b32_dpp v35, v19 row_ror:2 row_mask:0xf bank_mask:0xf
	v_pk_mul_f32 v[14:15], v[14:15], v[180:181]
	v_mov_b32_dpp v28, v16 row_shr:1 row_mask:0xf bank_mask:0xf
	v_mov_b32_dpp v29, v17 row_shr:1 row_mask:0xf bank_mask:0xf
	v_mov_b32_dpp v32, v20 row_ror:1 row_mask:0xf bank_mask:0xf
	v_mov_b32_dpp v33, v21 row_ror:1 row_mask:0xf bank_mask:0xf
	v_mov_b32_dpp v18, v20 row_ror:2 row_mask:0xf bank_mask:0xf
	v_mov_b32_dpp v19, v21 row_ror:2 row_mask:0xf bank_mask:0xf
	v_pk_fma_f32 v[20:21], v[92:93], v[22:23], v[96:97]
	v_mov_b32_dpp v30, v14 row_shr:2 row_mask:0xf bank_mask:0xf
	v_mov_b32_dpp v31, v15 row_shr:2 row_mask:0xf bank_mask:0xf
	v_pk_fma_f32 v[20:21], v[88:89], v[28:29], v[20:21]
	v_mov_b32_dpp v26, v14 row_shr:1 row_mask:0xf bank_mask:0xf
	v_mov_b32_dpp v27, v15 row_shr:1 row_mask:0xf bank_mask:0xf
	v_pk_fma_f32 v[22:23], v[90:91], v[30:31], v[94:95]
	v_pk_fma_f32 v[20:21], v[16:17], v[84:85], v[20:21]
	v_pk_fma_f32 v[22:23], v[86:87], v[26:27], v[22:23]
	v_mul_f32_e32 v26, 0xbfb8aa3b, v21
	v_exp_f32_e32 v26, v26
	v_mul_f32_e32 v27, 0xbfb8aa3b, v20
	v_exp_f32_e32 v28, v27
	v_pk_fma_f32 v[22:23], v[14:15], v[82:83], v[22:23]
	v_add_f32_e32 v26, 1.0, v26
	v_rcp_f32_e32 v27, v26
	v_add_f32_e32 v26, 1.0, v28
	v_mul_f32_e32 v28, 0xbfb8aa3b, v23
	v_exp_f32_e32 v28, v28
	v_mul_f32_e32 v29, 0xbfb8aa3b, v22
	v_exp_f32_e32 v30, v29
	v_rcp_f32_e32 v26, v26
	v_add_f32_e32 v28, 1.0, v28
	v_rcp_f32_e32 v29, v28
	v_add_f32_e32 v28, 1.0, v30
	v_pk_mul_f32 v[10:11], v[10:11], v[180:181]
	v_mov_b32_dpp v18, v12 row_shr:2 row_mask:0xf bank_mask:0xf
	v_mov_b32_dpp v19, v13 row_shr:2 row_mask:0xf bank_mask:0xf
	v_rcp_f32_e32 v28, v28
	v_mov_b32_dpp v32, v12 row_shr:1 row_mask:0xf bank_mask:0xf
	v_mov_b32_dpp v33, v13 row_shr:1 row_mask:0xf bank_mask:0xf
	v_mov_b32_dpp v34, v10 row_shr:2 row_mask:0xf bank_mask:0xf
	v_mov_b32_dpp v35, v11 row_shr:2 row_mask:0xf bank_mask:0xf
	v_pk_fma_f32 v[18:19], v[76:77], v[18:19], v[80:81]
	v_mov_b32_dpp v24, v10 row_shr:1 row_mask:0xf bank_mask:0xf
	v_mov_b32_dpp v25, v11 row_shr:1 row_mask:0xf bank_mask:0xf
	v_pk_fma_f32 v[30:31], v[74:75], v[34:35], v[78:79]
	v_pk_fma_f32 v[18:19], v[68:69], v[32:33], v[18:19]
	v_pk_fma_f32 v[24:25], v[66:67], v[24:25], v[30:31]
	v_pk_fma_f32 v[18:19], v[12:13], v[72:73], v[18:19]
	v_pk_mul_f32 v[20:21], v[20:21], v[26:27]
	v_pk_fma_f32 v[24:25], v[10:11], v[70:71], v[24:25]
	v_pk_mul_f32 v[22:23], v[22:23], v[28:29]
	v_pk_mul_f32 v[18:19], v[20:21], v[18:19]
	v_pk_mul_f32 v[22:23], v[22:23], v[24:25]
	v_cvt_pk_bf16_f32 v21, v18, v19
	v_mov_b32_e32 v18, v178
	v_mov_b32_e32 v19, v178
	v_cvt_pk_bf16_f32 v20, v22, v23
	v_pk_mul_f32 v[8:9], v[8:9], v[18:19]
	v_pk_mul_f32 v[4:5], v[4:5], v[18:19]
	global_store_dwordx2 v[118:119], v[20:21], off offset:128
	v_mov_b32_dpp v18, v14 row_ror:1 row_mask:0xf bank_mask:0xf
	v_mov_b32_dpp v19, v15 row_ror:1 row_mask:0xf bank_mask:0xf
	v_mov_b32_dpp v22, v14 row_ror:2 row_mask:0xf bank_mask:0xf
	v_mov_b32_dpp v23, v15 row_ror:2 row_mask:0xf bank_mask:0xf
	v_mov_b32_dpp v20, v16 row_ror:1 row_mask:0xf bank_mask:0xf
	v_mov_b32_dpp v21, v17 row_ror:1 row_mask:0xf bank_mask:0xf
	v_mov_b32_dpp v14, v16 row_ror:2 row_mask:0xf bank_mask:0xf
	v_mov_b32_dpp v15, v17 row_ror:2 row_mask:0xf bank_mask:0xf
	v_mov_b32_e32 v179, v178
	v_mov_b32_dpp v14, v8 row_shr:2 row_mask:0xf bank_mask:0xf
	v_mov_b32_dpp v15, v9 row_shr:2 row_mask:0xf bank_mask:0xf
	v_mov_b32_dpp v16, v10 row_ror:1 row_mask:0xf bank_mask:0xf
	v_mov_b32_dpp v17, v11 row_ror:1 row_mask:0xf bank_mask:0xf
	v_mov_b32_dpp v26, v10 row_ror:2 row_mask:0xf bank_mask:0xf
	v_mov_b32_dpp v27, v11 row_ror:2 row_mask:0xf bank_mask:0xf
	v_pk_mul_f32 v[6:7], v[6:7], v[178:179]
	v_mov_b32_dpp v20, v8 row_shr:1 row_mask:0xf bank_mask:0xf
	v_mov_b32_dpp v21, v9 row_shr:1 row_mask:0xf bank_mask:0xf
	v_mov_b32_dpp v24, v12 row_ror:1 row_mask:0xf bank_mask:0xf
	v_mov_b32_dpp v25, v13 row_ror:1 row_mask:0xf bank_mask:0xf
	v_mov_b32_dpp v10, v12 row_ror:2 row_mask:0xf bank_mask:0xf
	v_mov_b32_dpp v11, v13 row_ror:2 row_mask:0xf bank_mask:0xf
	v_pk_fma_f32 v[12:13], v[92:93], v[14:15], v[96:97]
	v_mov_b32_dpp v22, v6 row_shr:2 row_mask:0xf bank_mask:0xf
	v_mov_b32_dpp v23, v7 row_shr:2 row_mask:0xf bank_mask:0xf
	v_pk_fma_f32 v[12:13], v[88:89], v[20:21], v[12:13]
	v_mov_b32_dpp v18, v6 row_shr:1 row_mask:0xf bank_mask:0xf
	v_mov_b32_dpp v19, v7 row_shr:1 row_mask:0xf bank_mask:0xf
	v_pk_fma_f32 v[14:15], v[90:91], v[22:23], v[94:95]
	v_pk_fma_f32 v[12:13], v[8:9], v[84:85], v[12:13]
	v_pk_fma_f32 v[14:15], v[86:87], v[18:19], v[14:15]
	v_mul_f32_e32 v18, 0xbfb8aa3b, v13
	v_exp_f32_e32 v18, v18
	v_mul_f32_e32 v19, 0xbfb8aa3b, v12
	v_exp_f32_e32 v20, v19
	v_pk_fma_f32 v[14:15], v[6:7], v[82:83], v[14:15]
	v_add_f32_e32 v18, 1.0, v18
	v_rcp_f32_e32 v19, v18
	v_add_f32_e32 v18, 1.0, v20
	v_mul_f32_e32 v20, 0xbfb8aa3b, v15
	v_exp_f32_e32 v20, v20
	v_mul_f32_e32 v21, 0xbfb8aa3b, v14
	v_exp_f32_e32 v22, v21
	v_pk_mul_f32 v[2:3], v[2:3], v[178:179]
	v_add_f32_e32 v20, 1.0, v20
	v_rcp_f32_e32 v21, v20
	v_add_f32_e32 v20, 1.0, v22
	v_rcp_f32_e32 v18, v18
	v_rcp_f32_e32 v20, v20
	v_mov_b32_dpp v26, v2 row_shr:2 row_mask:0xf bank_mask:0xf
	v_mov_b32_dpp v27, v3 row_shr:2 row_mask:0xf bank_mask:0xf
	v_mov_b32_dpp v10, v4 row_shr:2 row_mask:0xf bank_mask:0xf
	v_mov_b32_dpp v11, v5 row_shr:2 row_mask:0xf bank_mask:0xf
	v_mov_b32_dpp v16, v2 row_shr:1 row_mask:0xf bank_mask:0xf
	v_mov_b32_dpp v17, v3 row_shr:1 row_mask:0xf bank_mask:0xf
	v_mov_b32_dpp v24, v4 row_shr:1 row_mask:0xf bank_mask:0xf
	v_mov_b32_dpp v25, v5 row_shr:1 row_mask:0xf bank_mask:0xf
	v_pk_fma_f32 v[10:11], v[76:77], v[10:11], v[80:81]
	v_pk_fma_f32 v[22:23], v[74:75], v[26:27], v[78:79]
	v_pk_fma_f32 v[10:11], v[68:69], v[24:25], v[10:11]
	v_pk_fma_f32 v[16:17], v[66:67], v[16:17], v[22:23]
	v_pk_fma_f32 v[10:11], v[4:5], v[72:73], v[10:11]
	v_pk_fma_f32 v[16:17], v[2:3], v[70:71], v[16:17]
	v_pk_mul_f32 v[14:15], v[14:15], v[20:21]
	v_pk_mul_f32 v[12:13], v[12:13], v[18:19]
	v_pk_mul_f32 v[14:15], v[14:15], v[16:17]
	v_pk_mul_f32 v[10:11], v[12:13], v[10:11]
	v_cvt_pk_bf16_f32 v12, v14, v15
	v_cvt_pk_bf16_f32 v13, v10, v11
	global_store_dwordx2 v[120:121], v[12:13], off offset:128
	s_and_saveexec_b64 s[60:61], s[10:11]
	s_cbranch_execz .LBB0_1445
	v_lshl_add_u64 v[10:11], v[122:123], 2, v[102:103]
	global_store_dwordx4 v[104:105], v[6:9], off offset:256
	s_nop 1
	v_add_co_u32_e32 v6, vcc, 0x2000, v10
	s_nop 1
	v_addc_co_u32_e32 v7, vcc, 0, v11, vcc
	global_store_dwordx4 v[6:7], v[2:5], off offset:3072
